# stack + attention max reduction as 2x8 v_max3 chains (was 56 ops per 32 scores)
# speedup vs baseline: 1.0238x; 1.0023x over previous
.LBB0_814:
	s_nop 9
	v_max3_f32 v0, v65, v81, v66
	v_max3_f32 v2, v72, v88, v73
	v_max3_f32 v0, v0, v82, v67
	v_max3_f32 v2, v2, v89, v74
	v_max3_f32 v0, v0, v83, v80
	v_max3_f32 v2, v2, v90, v75
	v_max3_f32 v0, v0, v64, v68
	v_max3_f32 v2, v2, v91, v76
	v_max3_f32 v0, v0, v84, v69
	v_max3_f32 v2, v2, v92, v77
	v_max3_f32 v0, v0, v85, v70
	v_max3_f32 v2, v2, v93, v78
	v_max3_f32 v0, v0, v86, v71
	v_max3_f32 v2, v2, v94, v79
	v_max3_f32 v0, v0, v87, v87
	v_max3_f32 v2, v2, v95, v95
	v_max_f32_e32 v0, v0, v2
	v_mov_b32_e32 v2, v0
	s_nop 1
	v_permlane32_swap_b32_e32 v0, v2
	v_max_f32_e32 v2, v2, v2
	v_max_f32_e32 v0, v0, v0
	v_max_f32_e32 v0, v0, v2
	v_cmp_lt_f32_e32 vcc, s57, v0
	s_cbranch_vccz .LBB0_816
	v_max_f32_e32 v0, v0, v0
	v_max_f32_e32 v0, 0, v0
	v_exp_f32_e64 v2, -v0
	v_add_f32_e32 v165, v165, v0
	v_xor_b32_e32 v48, 0x80000000, v165
	v_pk_add_f32 v[80:81], v[80:81], v[0:1] op_sel_hi:[1,0] neg_lo:[0,1] neg_hi:[0,1]
	v_mul_f32_e32 v163, v163, v2
	v_pk_add_f32 v[64:65], v[64:65], v[0:1] op_sel_hi:[1,0] neg_lo:[0,1] neg_hi:[0,1]
	v_pk_add_f32 v[82:83], v[82:83], v[0:1] op_sel_hi:[1,0] neg_lo:[0,1] neg_hi:[0,1]
	v_pk_add_f32 v[66:67], v[66:67], v[0:1] op_sel_hi:[1,0] neg_lo:[0,1] neg_hi:[0,1]
	v_pk_add_f32 v[84:85], v[84:85], v[0:1] op_sel_hi:[1,0] neg_lo:[0,1] neg_hi:[0,1]
	v_pk_add_f32 v[68:69], v[68:69], v[0:1] op_sel_hi:[1,0] neg_lo:[0,1] neg_hi:[0,1]
	v_pk_add_f32 v[86:87], v[86:87], v[0:1] op_sel_hi:[1,0] neg_lo:[0,1] neg_hi:[0,1]
	v_pk_add_f32 v[70:71], v[70:71], v[0:1] op_sel_hi:[1,0] neg_lo:[0,1] neg_hi:[0,1]
	v_pk_add_f32 v[88:89], v[88:89], v[0:1] op_sel_hi:[1,0] neg_lo:[0,1] neg_hi:[0,1]
	v_pk_add_f32 v[72:73], v[72:73], v[0:1] op_sel_hi:[1,0] neg_lo:[0,1] neg_hi:[0,1]
	v_pk_add_f32 v[90:91], v[90:91], v[0:1] op_sel_hi:[1,0] neg_lo:[0,1] neg_hi:[0,1]
	v_pk_add_f32 v[74:75], v[74:75], v[0:1] op_sel_hi:[1,0] neg_lo:[0,1] neg_hi:[0,1]
	v_pk_add_f32 v[92:93], v[92:93], v[0:1] op_sel_hi:[1,0] neg_lo:[0,1] neg_hi:[0,1]
	v_pk_add_f32 v[76:77], v[76:77], v[0:1] op_sel_hi:[1,0] neg_lo:[0,1] neg_hi:[0,1]
	v_pk_add_f32 v[94:95], v[94:95], v[0:1] op_sel_hi:[1,0] neg_lo:[0,1] neg_hi:[0,1]
	v_pk_add_f32 v[78:79], v[78:79], v[0:1] op_sel_hi:[1,0] neg_lo:[0,1] neg_hi:[0,1]
	v_pk_mul_f32 v[46:47], v[46:47], v[2:3] op_sel_hi:[1,0]
	v_pk_mul_f32 v[44:45], v[44:45], v[2:3] op_sel_hi:[1,0]
	v_pk_mul_f32 v[42:43], v[42:43], v[2:3] op_sel_hi:[1,0]
	v_pk_mul_f32 v[40:41], v[40:41], v[2:3] op_sel_hi:[1,0]
	v_pk_mul_f32 v[38:39], v[38:39], v[2:3] op_sel_hi:[1,0]
	v_pk_mul_f32 v[36:37], v[36:37], v[2:3] op_sel_hi:[1,0]
	v_pk_mul_f32 v[34:35], v[34:35], v[2:3] op_sel_hi:[1,0]
	v_pk_mul_f32 v[32:33], v[32:33], v[2:3] op_sel_hi:[1,0]
	v_pk_mul_f32 v[30:31], v[30:31], v[2:3] op_sel_hi:[1,0]
	v_pk_mul_f32 v[28:29], v[28:29], v[2:3] op_sel_hi:[1,0]
	v_pk_mul_f32 v[26:27], v[26:27], v[2:3] op_sel_hi:[1,0]
	v_pk_mul_f32 v[24:25], v[24:25], v[2:3] op_sel_hi:[1,0]
	v_pk_mul_f32 v[22:23], v[22:23], v[2:3] op_sel_hi:[1,0]
	v_pk_mul_f32 v[20:21], v[20:21], v[2:3] op_sel_hi:[1,0]
	v_pk_mul_f32 v[18:19], v[18:19], v[2:3] op_sel_hi:[1,0]
	v_pk_mul_f32 v[16:17], v[16:17], v[2:3] op_sel_hi:[1,0]
	v_mov_b32_e32 v49, v48
	v_mov_b32_e32 v50, v48
	v_mov_b32_e32 v51, v48
	v_mov_b32_e32 v52, v48
	v_mov_b32_e32 v53, v48
	v_mov_b32_e32 v54, v48
	v_mov_b32_e32 v55, v48
	v_mov_b32_e32 v56, v48
	v_mov_b32_e32 v57, v48
	v_mov_b32_e32 v58, v48
	v_mov_b32_e32 v59, v48
	v_mov_b32_e32 v60, v48
	v_mov_b32_e32 v61, v48
	v_mov_b32_e32 v62, v48
	v_mov_b32_e32 v63, v48

.LBB0_840:
	s_nop 9
	v_max3_f32 v0, v65, v81, v66
	v_max3_f32 v2, v72, v88, v73
	v_max3_f32 v0, v0, v82, v67
	v_max3_f32 v2, v2, v89, v74
	v_max3_f32 v0, v0, v83, v80
	v_max3_f32 v2, v2, v90, v75
	v_max3_f32 v0, v0, v64, v68
	v_max3_f32 v2, v2, v91, v76
	v_max3_f32 v0, v0, v84, v69
	v_max3_f32 v2, v2, v92, v77
	v_max3_f32 v0, v0, v85, v70
	v_max3_f32 v2, v2, v93, v78
	v_max3_f32 v0, v0, v86, v71
	v_max3_f32 v2, v2, v94, v79
	v_max3_f32 v0, v0, v87, v87
	v_max3_f32 v2, v2, v95, v95
	v_max_f32_e32 v0, v0, v2
	v_mov_b32_e32 v2, v0
	s_nop 1
	v_permlane32_swap_b32_e32 v0, v2
	v_max_f32_e32 v2, v2, v2
	v_max_f32_e32 v0, v0, v0
	v_max_f32_e32 v0, v0, v2
	v_cmp_lt_f32_e32 vcc, s57, v0
	s_cbranch_vccz .LBB0_807
	v_max_f32_e32 v0, v0, v0
	v_max_f32_e32 v0, 0, v0
	v_exp_f32_e64 v2, -v0
	v_add_f32_e32 v165, v165, v0
	v_xor_b32_e32 v48, 0x80000000, v165
	v_pk_add_f32 v[80:81], v[80:81], v[0:1] op_sel_hi:[1,0] neg_lo:[0,1] neg_hi:[0,1]
	v_mul_f32_e32 v163, v163, v2
	v_pk_add_f32 v[64:65], v[64:65], v[0:1] op_sel_hi:[1,0] neg_lo:[0,1] neg_hi:[0,1]
	v_pk_add_f32 v[82:83], v[82:83], v[0:1] op_sel_hi:[1,0] neg_lo:[0,1] neg_hi:[0,1]
	v_pk_add_f32 v[66:67], v[66:67], v[0:1] op_sel_hi:[1,0] neg_lo:[0,1] neg_hi:[0,1]
	v_pk_add_f32 v[84:85], v[84:85], v[0:1] op_sel_hi:[1,0] neg_lo:[0,1] neg_hi:[0,1]
	v_pk_add_f32 v[68:69], v[68:69], v[0:1] op_sel_hi:[1,0] neg_lo:[0,1] neg_hi:[0,1]
	v_pk_add_f32 v[86:87], v[86:87], v[0:1] op_sel_hi:[1,0] neg_lo:[0,1] neg_hi:[0,1]
	v_pk_add_f32 v[70:71], v[70:71], v[0:1] op_sel_hi:[1,0] neg_lo:[0,1] neg_hi:[0,1]
	v_pk_add_f32 v[88:89], v[88:89], v[0:1] op_sel_hi:[1,0] neg_lo:[0,1] neg_hi:[0,1]
	v_pk_add_f32 v[72:73], v[72:73], v[0:1] op_sel_hi:[1,0] neg_lo:[0,1] neg_hi:[0,1]
	v_pk_add_f32 v[90:91], v[90:91], v[0:1] op_sel_hi:[1,0] neg_lo:[0,1] neg_hi:[0,1]
	v_pk_add_f32 v[74:75], v[74:75], v[0:1] op_sel_hi:[1,0] neg_lo:[0,1] neg_hi:[0,1]
	v_pk_add_f32 v[92:93], v[92:93], v[0:1] op_sel_hi:[1,0] neg_lo:[0,1] neg_hi:[0,1]
	v_pk_add_f32 v[76:77], v[76:77], v[0:1] op_sel_hi:[1,0] neg_lo:[0,1] neg_hi:[0,1]
	v_pk_add_f32 v[94:95], v[94:95], v[0:1] op_sel_hi:[1,0] neg_lo:[0,1] neg_hi:[0,1]
	v_pk_add_f32 v[78:79], v[78:79], v[0:1] op_sel_hi:[1,0] neg_lo:[0,1] neg_hi:[0,1]
	v_pk_mul_f32 v[46:47], v[46:47], v[2:3] op_sel_hi:[1,0]
	v_pk_mul_f32 v[44:45], v[44:45], v[2:3] op_sel_hi:[1,0]
	v_pk_mul_f32 v[42:43], v[42:43], v[2:3] op_sel_hi:[1,0]
	v_pk_mul_f32 v[40:41], v[40:41], v[2:3] op_sel_hi:[1,0]
	v_pk_mul_f32 v[38:39], v[38:39], v[2:3] op_sel_hi:[1,0]
	v_pk_mul_f32 v[36:37], v[36:37], v[2:3] op_sel_hi:[1,0]
	v_pk_mul_f32 v[34:35], v[34:35], v[2:3] op_sel_hi:[1,0]
	v_pk_mul_f32 v[32:33], v[32:33], v[2:3] op_sel_hi:[1,0]
	v_pk_mul_f32 v[30:31], v[30:31], v[2:3] op_sel_hi:[1,0]
	v_pk_mul_f32 v[28:29], v[28:29], v[2:3] op_sel_hi:[1,0]
	v_pk_mul_f32 v[26:27], v[26:27], v[2:3] op_sel_hi:[1,0]
	v_pk_mul_f32 v[24:25], v[24:25], v[2:3] op_sel_hi:[1,0]
	v_pk_mul_f32 v[22:23], v[22:23], v[2:3] op_sel_hi:[1,0]
	v_pk_mul_f32 v[20:21], v[20:21], v[2:3] op_sel_hi:[1,0]
	v_pk_mul_f32 v[18:19], v[18:19], v[2:3] op_sel_hi:[1,0]
	v_pk_mul_f32 v[16:17], v[16:17], v[2:3] op_sel_hi:[1,0]
	v_mov_b32_e32 v49, v48
	v_mov_b32_e32 v50, v48
	v_mov_b32_e32 v51, v48
	v_mov_b32_e32 v52, v48
	v_mov_b32_e32 v53, v48
	v_mov_b32_e32 v54, v48
	v_mov_b32_e32 v55, v48
	v_mov_b32_e32 v56, v48
	v_mov_b32_e32 v57, v48
	v_mov_b32_e32 v58, v48
	v_mov_b32_e32 v59, v48
	v_mov_b32_e32 v60, v48
	v_mov_b32_e32 v61, v48
	v_mov_b32_e32 v62, v48
	v_mov_b32_e32 v63, v48
	s_branch .LBB0_807

.LBB0_849:
	s_cmpk_gt_i32 s68, 0x3ff
	s_mov_b64 s[6:7], -1
	s_cbranch_scc0 .LBB0_860
	s_lshl_b32 s4, s68, 8
	s_lshl_b32 s2, s68, 3
	v_mbcnt_lo_u32_b32 v3, -1, 0
	v_mbcnt_hi_u32_b32 v3, -1, v3
	s_and_b32 s4, s4, 0x700
	v_or_b32_e32 v0, v3, v128
	s_and_b32 s2, s2, 0x7fffffc0
	s_or_b32 s8, s4, 0x4000
	v_ashrrev_i32_e32 v2, 3, v0
	v_and_b32_e32 v20, 7, v3
	s_add_i32 s6, s2, 0xffffe400
	s_add_i32 s7, s2, 0xffffe800
	v_mov_b64_e32 v[12:13], s[80:81]
	v_add_u32_e32 v0, s8, v2
	v_lshlrev_b32_e32 v4, 3, v20
	v_mad_i64_i32 v[60:61], s[4:5], v0, s44, v[12:13]
	v_or_b32_e32 v0, s6, v4
	v_or_b32_e32 v62, s7, v4
	v_mov_b32_e32 v63, v1
	v_lshlrev_b64 v[14:15], 1, v[0:1]
	v_lshlrev_b64 v[16:17], 1, v[62:63]
	v_lshl_add_u64 v[4:5], v[60:61], 0, v[14:15]
	v_lshl_add_u64 v[8:9], v[60:61], 0, v[16:17]
	global_load_dwordx4 v[4:7], v[4:5], off
	s_nop 0
	global_load_dwordx4 v[8:11], v[8:9], off
	s_add_i32 s66, s2, 0xffffe000
	v_readlane_b32 s2, v254, 18
	v_and_b32_e32 v21, 31, v3
	s_add_i32 s8, s8, s2
	v_or_b32_e32 v114, s8, v21
	v_mad_u64_u32 v[12:13], s[4:5], v114, s44, v[12:13]
	v_and_b32_e32 v18, 0xffffffe0, v3
	v_lshl_add_u64 v[12:13], s[66:67], 1, v[12:13]
	v_ashrrev_i32_e32 v19, 31, v18
	v_lshl_add_u64 v[12:13], v[18:19], 1, v[12:13]
	global_load_dwordx4 v[90:93], v[12:13], off
	global_load_dwordx4 v[86:89], v[12:13], off offset:16
	global_load_dwordx4 v[82:85], v[12:13], off offset:32
	v_lshlrev_b32_e32 v18, 1, v3
	v_and_b32_e32 v18, 0xffffffc0, v18
	s_movk_i32 s5, 0x90
	s_mov_b64 s[6:7], 0x60000
	s_waitcnt vmcnt(15)
	v_mad_u32_u24 v66, v21, s5, v18
	v_lshl_add_u64 v[18:19], v[60:61], 0, s[6:7]
	v_lshl_add_u64 v[22:23], v[18:19], 0, v[14:15]
	v_lshl_add_u64 v[18:19], v[18:19], 0, v[16:17]
	global_load_dwordx4 v[56:59], v[22:23], off
	global_load_dwordx4 v[52:55], v[18:19], off
	global_load_dwordx4 v[94:97], v[12:13], off offset:48
	v_mul_lo_u32 v2, v2, s5
	s_mov_b64 s[6:7], 0xc0000
	s_add_i32 s2, 0, 0x18000
	v_lshl_add_u32 v64, v20, 4, v2
	v_add_u32_e32 v65, 0, v66
	v_lshl_add_u64 v[20:21], v[60:61], 0, s[6:7]
	v_add_u32_e32 v124, s2, v64
	v_add_u32_e32 v67, 0, v64
	v_add_u32_e32 v123, 0x19200, v65
	v_lshl_add_u64 v[14:15], v[20:21], 0, v[14:15]
	v_add_u32_e32 v125, 0x1a400, v67
	v_lshl_add_u64 v[16:17], v[20:21], 0, v[16:17]
	s_waitcnt lgkmcnt(0)
	s_barrier
	global_load_dwordx4 v[106:109], v[14:15], off
	global_load_dwordx4 v[110:113], v[16:17], off
	v_add_u32_e32 v127, s2, v66
	s_movk_i32 s4, 0x90
	s_waitcnt vmcnt(9)
	ds_write_b128 v124, v[4:7]
	s_waitcnt vmcnt(8)
	ds_write_b128 v125, v[8:11]
	s_waitcnt lgkmcnt(0)
	s_barrier
	ds_read_b128 v[4:7], v123
	s_waitcnt vmcnt(7) lgkmcnt(0)
	v_mfma_f32_32x32x16_bf16 v[20:35], v[4:7], v[90:93], 0
	ds_read_b128 v[4:7], v127
	s_waitcnt lgkmcnt(0)
	v_mfma_f32_32x32x16_bf16 v[36:51], v[4:7], v[90:93], 0
	ds_read_b128 v[4:7], v123 offset:16
	s_waitcnt vmcnt(6) lgkmcnt(0)
	v_mfma_f32_32x32x16_bf16 v[20:35], v[4:7], v[86:89], v[20:35]
	ds_read_b128 v[4:7], v127 offset:16
	s_waitcnt lgkmcnt(0)
	v_mfma_f32_32x32x16_bf16 v[36:51], v[4:7], v[86:89], v[36:51]
	ds_read_b128 v[4:7], v123 offset:32
	s_waitcnt vmcnt(5) lgkmcnt(0)
	v_mfma_f32_32x32x16_bf16 v[20:35], v[4:7], v[82:85], v[20:35]
	ds_read_b128 v[4:7], v127 offset:32
	s_waitcnt lgkmcnt(0)
	v_mfma_f32_32x32x16_bf16 v[36:51], v[4:7], v[82:85], v[36:51]
	ds_read_b128 v[4:7], v123 offset:48
	s_waitcnt vmcnt(2) lgkmcnt(0)
	v_mfma_f32_32x32x16_bf16 v[20:35], v[4:7], v[94:97], v[20:35]
	ds_read_b128 v[4:7], v127 offset:48
	s_waitcnt lgkmcnt(0)
	v_mfma_f32_32x32x16_bf16 v[36:51], v[4:7], v[94:97], v[36:51]
	s_nop 8
	v_max3_f32 v2, v21, v22, v23
	v_max3_f32 v4, v28, v44, v29
	v_max3_f32 v2, v2, v24, v25
	v_max3_f32 v4, v4, v45, v30
	v_max3_f32 v2, v2, v26, v27
	v_max3_f32 v4, v4, v46, v31
	v_max3_f32 v2, v2, v37, v38
	v_max3_f32 v4, v4, v47, v32
	v_max3_f32 v2, v2, v39, v40
	v_max3_f32 v4, v4, v48, v33
	v_max3_f32 v2, v2, v41, v36
	v_max3_f32 v4, v4, v49, v34
	v_max3_f32 v2, v2, v20, v42
	v_max3_f32 v4, v4, v50, v35
	v_max3_f32 v2, v2, v43, v43
	v_max3_f32 v4, v4, v51, v51
	v_max_f32_e32 v2, v2, v4
	v_mov_b32_e32 v4, v2
	s_nop 1
	v_permlane32_swap_b32_e32 v2, v4
	v_max_f32_e32 v4, v4, v4
	v_max_f32_e32 v2, v2, v2
	v_max_f32_e32 v2, v2, v4
	v_cmp_lt_f32_e32 vcc, s57, v2
	s_cbranch_vccz .LBB0_852
	v_max_f32_e32 v2, v2, v2
	v_max_f32_e32 v4, 0, v2
	v_exp_f32_e64 v2, -v4
	v_add_f32_e32 v126, 0, v4
	v_xor_b32_e32 v18, 0x80000000, v126
	v_pk_add_f32 v[36:37], v[36:37], v[4:5] op_sel_hi:[1,0] neg_lo:[0,1] neg_hi:[0,1]
	v_mul_f32_e32 v2, 0, v2
	v_pk_add_f32 v[20:21], v[20:21], v[4:5] op_sel_hi:[1,0] neg_lo:[0,1] neg_hi:[0,1]
	v_pk_add_f32 v[38:39], v[38:39], v[4:5] op_sel_hi:[1,0] neg_lo:[0,1] neg_hi:[0,1]
	v_pk_add_f32 v[22:23], v[22:23], v[4:5] op_sel_hi:[1,0] neg_lo:[0,1] neg_hi:[0,1]
	v_pk_add_f32 v[40:41], v[40:41], v[4:5] op_sel_hi:[1,0] neg_lo:[0,1] neg_hi:[0,1]
	v_pk_add_f32 v[24:25], v[24:25], v[4:5] op_sel_hi:[1,0] neg_lo:[0,1] neg_hi:[0,1]
	v_pk_add_f32 v[42:43], v[42:43], v[4:5] op_sel_hi:[1,0] neg_lo:[0,1] neg_hi:[0,1]
	v_pk_add_f32 v[26:27], v[26:27], v[4:5] op_sel_hi:[1,0] neg_lo:[0,1] neg_hi:[0,1]
	v_pk_add_f32 v[44:45], v[44:45], v[4:5] op_sel_hi:[1,0] neg_lo:[0,1] neg_hi:[0,1]
	v_pk_add_f32 v[28:29], v[28:29], v[4:5] op_sel_hi:[1,0] neg_lo:[0,1] neg_hi:[0,1]
	v_pk_add_f32 v[46:47], v[46:47], v[4:5] op_sel_hi:[1,0] neg_lo:[0,1] neg_hi:[0,1]
	v_pk_add_f32 v[30:31], v[30:31], v[4:5] op_sel_hi:[1,0] neg_lo:[0,1] neg_hi:[0,1]
	v_pk_add_f32 v[48:49], v[48:49], v[4:5] op_sel_hi:[1,0] neg_lo:[0,1] neg_hi:[0,1]
	v_pk_add_f32 v[32:33], v[32:33], v[4:5] op_sel_hi:[1,0] neg_lo:[0,1] neg_hi:[0,1]
	v_pk_add_f32 v[50:51], v[50:51], v[4:5] op_sel_hi:[1,0] neg_lo:[0,1] neg_hi:[0,1]
	v_pk_add_f32 v[34:35], v[34:35], v[4:5] op_sel_hi:[1,0] neg_lo:[0,1] neg_hi:[0,1]
	s_branch .LBB0_853

.LBB0_853:
	v_exp_f32_e32 v103, v36
	v_exp_f32_e32 v116, v20
	v_exp_f32_e32 v20, v37
	v_exp_f32_e32 v68, v21
	v_mov_b32_e32 v21, v1
	v_add_f32_e32 v69, v116, v103
	v_exp_f32_e32 v70, v23
	v_pk_add_f32 v[8:9], v[68:69], v[20:21]
	v_exp_f32_e32 v21, v38
	v_pk_add_f32 v[36:37], v[8:9], v[8:9] op_sel_hi:[0,1]
	v_exp_f32_e32 v69, v22
	v_exp_f32_e32 v36, v39
	v_exp_f32_e32 v72, v25
	v_exp_f32_e32 v74, v27
	v_add_f32_e32 v71, v69, v21
	v_pk_add_f32 v[10:11], v[70:71], v[36:37]
	v_exp_f32_e32 v37, v40
	v_pk_add_f32 v[22:23], v[10:11], v[10:11] op_sel_hi:[0,1]
	v_exp_f32_e32 v71, v24
	v_exp_f32_e32 v22, v41
	v_exp_f32_e32 v117, v28
	v_exp_f32_e32 v78, v29
	v_add_f32_e32 v73, v71, v37
	v_pk_add_f32 v[12:13], v[72:73], v[22:23]
	v_exp_f32_e32 v23, v42
	v_pk_add_f32 v[24:25], v[12:13], v[12:13] op_sel_hi:[0,1]
	v_exp_f32_e32 v73, v26
	v_exp_f32_e32 v24, v43
	v_exp_f32_e32 v98, v31
	v_ashrrev_i32_e32 v118, 3, v3
	v_add_f32_e32 v75, v73, v23
	v_pk_add_f32 v[14:15], v[74:75], v[24:25]
	v_exp_f32_e32 v75, v44
	v_pk_add_f32 v[76:77], v[14:15], v[14:15] op_sel_hi:[0,1]
	v_exp_f32_e32 v76, v45
	v_lshrrev_b32_e32 v4, 2, v3
	v_add_f32_e32 v79, v117, v75
	v_and_b32_e32 v5, 16, v3
	v_pk_add_f32 v[16:17], v[78:79], v[76:77]
	v_exp_f32_e32 v77, v46
	v_pk_add_f32 v[80:81], v[16:17], v[16:17] op_sel_hi:[0,1]
	v_exp_f32_e32 v79, v30
	v_exp_f32_e32 v80, v47
	v_lshlrev_b32_e32 v3, 2, v3
	v_bfi_b32 v4, -4, v118, v4
	v_add_f32_e32 v99, v79, v77
	v_pk_add_f32 v[26:27], v[98:99], v[80:81]
	v_exp_f32_e32 v81, v48
	v_pk_add_f32 v[100:101], v[26:27], v[26:27] op_sel_hi:[0,1]
	v_exp_f32_e32 v99, v32
	v_and_or_b32 v3, v3, 12, v5
	v_exp_f32_e32 v100, v49
	v_exp_f32_e32 v102, v33
	v_mul_lo_u32 v4, v4, s4
	v_lshlrev_b32_e32 v3, 1, v3
	s_movk_i32 s2, 0x2400
	v_add3_u32 v19, v4, v3, s2
	v_add_u32_e32 v130, 0, v19
	v_cvt_pk_bf16_f32 v20, v103, v20
	v_add_f32_e32 v103, v99, v81
	v_add_u32_e32 v115, 0x18000, v130
	v_pk_add_f32 v[28:29], v[102:103], v[100:101]
	v_exp_f32_e32 v50, v50
	v_exp_f32_e32 v119, v34
	v_cvt_pk_bf16_f32 v21, v21, v36
	v_cvt_pk_bf16_f32 v22, v37, v22
	v_cvt_pk_bf16_f32 v23, v23, v24
	ds_read_b64_tr_b16 v[24:25], v115
	ds_read_b64_tr_b16 v[26:27], v115 offset:1152
	v_pk_add_f32 v[32:33], v[28:29], v[28:29] op_sel_hi:[0,1]
	v_exp_f32_e32 v32, v51
	v_exp_f32_e32 v104, v35
	v_mov_b32_e32 v3, v2
	v_mov_b32_e32 v4, v2
	v_mov_b32_e32 v5, v2
	v_mov_b32_e32 v6, v2
	v_mov_b32_e32 v7, v2
	v_mov_b32_e32 v8, v2
	v_mov_b32_e32 v9, v2
	v_mov_b32_e32 v10, v2
	v_mov_b32_e32 v11, v2
	v_mov_b32_e32 v12, v2
	v_mov_b32_e32 v13, v2
	v_mov_b32_e32 v14, v2
	v_mov_b32_e32 v15, v2
	v_mov_b32_e32 v16, v2
	v_mov_b32_e32 v17, v2
	v_add_f32_e32 v105, v119, v50
	ds_read_b64_tr_b16 v[30:31], v115 offset:1216
	ds_read_b64_tr_b16 v[28:29], v115 offset:64
	s_waitcnt lgkmcnt(2)
	v_mfma_f32_32x32x16_bf16 v[34:49], v[24:27], v[20:23], v[2:17]
	v_add_f32_e64 v24, v104, v32
	v_add_f32_e64 v25, v105, v33
	v_readlane_b32 s2, v254, 45
	v_pk_add_f32 v[24:25], v[24:25], v[24:25] op_sel:[0,1] op_sel_hi:[1,0]
	s_mov_b64 s[4:5], 0x120000
	v_mov_b32_e32 v19, v24
	s_nop 1
	v_permlane32_swap_b32_e32 v24, v19
	v_add_f32_e32 v19, v24, v19
	v_add_f32_e32 v129, v2, v19
	s_waitcnt lgkmcnt(0)
	v_mfma_f32_32x32x16_bf16 v[2:17], v[28:31], v[20:23], v[2:17]
	v_cvt_pk_bf16_f32 v20, v75, v76
	v_cvt_pk_bf16_f32 v21, v77, v80
	v_cvt_pk_bf16_f32 v22, v81, v100
	v_cvt_pk_bf16_f32 v23, v50, v32
	ds_read_b64_tr_b16 v[24:25], v115 offset:2304
	ds_read_b64_tr_b16 v[26:27], v115 offset:3456
	ds_read_b64_tr_b16 v[28:29], v115 offset:3520
	v_add_u32_e32 v120, s2, v64
	v_add_u32_e32 v121, 0x1ec00, v67
	s_waitcnt lgkmcnt(1)
	v_mfma_f32_32x32x16_bf16 v[34:49], v[24:27], v[20:23], v[34:49]
	ds_read_b64_tr_b16 v[26:27], v115 offset:2368
	v_mov_b32_e32 v19, v18
	v_add_u32_e32 v122, s2, v66
	s_waitcnt lgkmcnt(0)
	v_mfma_f32_32x32x16_bf16 v[2:17], v[26:29], v[20:23], v[2:17]
	v_cvt_pk_bf16_f32 v22, v116, v68
	v_cvt_pk_bf16_f32 v23, v69, v70
	v_cvt_pk_bf16_f32 v24, v71, v72
	v_cvt_pk_bf16_f32 v25, v73, v74
	ds_read_b64_tr_b16 v[26:27], v115 offset:4608
	ds_read_b64_tr_b16 v[28:29], v115 offset:5760
	ds_read_b64_tr_b16 v[32:33], v115 offset:5824
	ds_read_b64_tr_b16 v[30:31], v115 offset:4672
	v_cvt_pk_bf16_f32 v68, v117, v78
	s_waitcnt lgkmcnt(2)
	v_mfma_f32_32x32x16_bf16 v[34:49], v[26:29], v[22:25], v[34:49]
	v_cvt_pk_bf16_f32 v69, v79, v98
	v_cvt_pk_bf16_f32 v70, v99, v102
	v_cvt_pk_bf16_f32 v71, v119, v104
	ds_read_b64_tr_b16 v[72:73], v115 offset:6912
	ds_read_b64_tr_b16 v[74:75], v115 offset:8064
	v_add_u32_e32 v119, 0x1da00, v65
	v_mov_b32_e32 v20, v18
	v_mov_b32_e32 v21, v18
	s_waitcnt lgkmcnt(2)
	v_mfma_f32_32x32x16_bf16 v[2:17], v[30:33], v[22:25], v[2:17]
	v_lshl_add_u64 v[32:33], v[60:61], 0, s[4:5]
	ds_read_b64_tr_b16 v[30:31], v115 offset:8128
	ds_read_b64_tr_b16 v[28:29], v115 offset:6976
	ds_write_b128 v120, v[56:59]
	ds_write_b128 v121, v[52:55]
	v_lshl_add_u64 v[50:51], v[0:1], 1, v[32:33]
	v_lshl_add_u64 v[32:33], v[62:63], 1, v[32:33]
	global_load_dwordx4 v[98:101], v[50:51], off
	global_load_dwordx4 v[102:105], v[32:33], off
	s_waitcnt lgkmcnt(4)
	v_mfma_f32_32x32x16_bf16 v[34:49], v[72:75], v[68:71], v[34:49]
	s_waitcnt lgkmcnt(0)
	s_barrier
	ds_read_b128 v[72:75], v119
	v_mov_b32_e32 v22, v18
	v_mov_b32_e32 v23, v18
	v_mov_b32_e32 v24, v18
	v_mov_b32_e32 v25, v18
	v_mov_b32_e32 v26, v18
	v_mfma_f32_32x32x16_bf16 v[2:17], v[28:31], v[68:71], v[2:17]
	v_mov_b32_e32 v27, v18
	v_mov_b32_e32 v28, v18
	v_mov_b32_e32 v29, v18
	v_mov_b32_e32 v30, v18
	v_mov_b32_e32 v31, v18
	v_mov_b32_e32 v32, v18
	v_mov_b32_e32 v33, v18
	ds_read_b128 v[68:71], v119 offset:16
	ds_read_b128 v[132:135], v122
	s_waitcnt lgkmcnt(2)
	v_mfma_f32_32x32x16_bf16 v[50:65], v[72:75], v[90:93], v[18:33]
	s_waitcnt lgkmcnt(1)
	v_mfma_f32_32x32x16_bf16 v[50:65], v[68:71], v[86:89], v[50:65]
	ds_read_b128 v[68:71], v119 offset:32
	s_waitcnt lgkmcnt(0)
	v_mfma_f32_32x32x16_bf16 v[50:65], v[68:71], v[82:85], v[50:65]
	ds_read_b128 v[68:71], v119 offset:48
	s_waitcnt lgkmcnt(0)
	v_mfma_f32_32x32x16_bf16 v[50:65], v[68:71], v[94:97], v[50:65]
	v_mfma_f32_32x32x16_bf16 v[66:81], v[132:135], v[90:93], v[18:33]
	ds_read_b128 v[132:135], v122 offset:16
	s_nop 9
	v_max_f32_e32 v0, v51, v51
	s_waitcnt lgkmcnt(0)
	v_mfma_f32_32x32x16_bf16 v[66:81], v[132:135], v[86:89], v[66:81]
	ds_read_b128 v[132:135], v122 offset:32
	s_waitcnt lgkmcnt(0)
	v_mfma_f32_32x32x16_bf16 v[66:81], v[132:135], v[82:85], v[66:81]
	ds_read_b128 v[132:135], v122 offset:48
	s_waitcnt lgkmcnt(0)
	v_mfma_f32_32x32x16_bf16 v[66:81], v[132:135], v[94:97], v[66:81]
	s_nop 11
	v_max3_f32 v0, v67, v0, v52
	v_max3_f32 v116, v58, v74, v59
	v_max3_f32 v0, v0, v68, v53
	v_max3_f32 v116, v116, v75, v60
	v_max3_f32 v0, v0, v69, v66
	v_max3_f32 v116, v116, v76, v61
	v_max3_f32 v0, v0, v50, v54
	v_max3_f32 v116, v116, v77, v62
	v_max3_f32 v0, v0, v70, v55
	v_max3_f32 v116, v116, v78, v63
	v_max3_f32 v0, v0, v71, v56
	v_max3_f32 v116, v116, v79, v64
	v_max3_f32 v0, v0, v72, v57
	v_max3_f32 v116, v116, v80, v65
	v_max3_f32 v0, v0, v73, v73
	v_max3_f32 v116, v116, v81, v81
	v_max_f32_e32 v0, v0, v116
	v_mov_b32_e32 v116, v0
	s_nop 1
	v_permlane32_swap_b32_e32 v0, v116
	v_max_f32_e32 v116, v116, v116
	v_max_f32_e32 v0, v0, v0
	v_max_f32_e32 v0, v0, v116
	v_cmp_lt_f32_e32 vcc, s57, v0
	s_cbranch_vccz .LBB0_855
	v_max_f32_e32 v0, v0, v0
	v_max_f32_e32 v0, 0, v0
	v_exp_f32_e64 v20, -v0
	v_add_f32_e32 v126, v126, v0
	v_xor_b32_e32 v18, 0x80000000, v126
	v_pk_add_f32 v[66:67], v[66:67], v[0:1] op_sel_hi:[1,0] neg_lo:[0,1] neg_hi:[0,1]
	v_mul_f32_e32 v129, v129, v20
	v_pk_add_f32 v[50:51], v[50:51], v[0:1] op_sel_hi:[1,0] neg_lo:[0,1] neg_hi:[0,1]
	v_pk_add_f32 v[68:69], v[68:69], v[0:1] op_sel_hi:[1,0] neg_lo:[0,1] neg_hi:[0,1]
	v_pk_add_f32 v[52:53], v[52:53], v[0:1] op_sel_hi:[1,0] neg_lo:[0,1] neg_hi:[0,1]
	v_pk_add_f32 v[70:71], v[70:71], v[0:1] op_sel_hi:[1,0] neg_lo:[0,1] neg_hi:[0,1]
	v_pk_add_f32 v[54:55], v[54:55], v[0:1] op_sel_hi:[1,0] neg_lo:[0,1] neg_hi:[0,1]
	v_pk_add_f32 v[72:73], v[72:73], v[0:1] op_sel_hi:[1,0] neg_lo:[0,1] neg_hi:[0,1]
	v_pk_add_f32 v[56:57], v[56:57], v[0:1] op_sel_hi:[1,0] neg_lo:[0,1] neg_hi:[0,1]
	v_pk_add_f32 v[74:75], v[74:75], v[0:1] op_sel_hi:[1,0] neg_lo:[0,1] neg_hi:[0,1]
	v_pk_add_f32 v[58:59], v[58:59], v[0:1] op_sel_hi:[1,0] neg_lo:[0,1] neg_hi:[0,1]
	v_pk_add_f32 v[76:77], v[76:77], v[0:1] op_sel_hi:[1,0] neg_lo:[0,1] neg_hi:[0,1]
	v_pk_add_f32 v[60:61], v[60:61], v[0:1] op_sel_hi:[1,0] neg_lo:[0,1] neg_hi:[0,1]
	v_pk_add_f32 v[78:79], v[78:79], v[0:1] op_sel_hi:[1,0] neg_lo:[0,1] neg_hi:[0,1]
	v_pk_add_f32 v[62:63], v[62:63], v[0:1] op_sel_hi:[1,0] neg_lo:[0,1] neg_hi:[0,1]
	v_pk_add_f32 v[80:81], v[80:81], v[0:1] op_sel_hi:[1,0] neg_lo:[0,1] neg_hi:[0,1]
	v_pk_add_f32 v[64:65], v[64:65], v[0:1] op_sel_hi:[1,0] neg_lo:[0,1] neg_hi:[0,1]
	v_pk_mul_f32 v[48:49], v[48:49], v[20:21] op_sel_hi:[1,0]
	v_pk_mul_f32 v[46:47], v[46:47], v[20:21] op_sel_hi:[1,0]
	v_pk_mul_f32 v[44:45], v[44:45], v[20:21] op_sel_hi:[1,0]
	v_pk_mul_f32 v[42:43], v[42:43], v[20:21] op_sel_hi:[1,0]
	v_pk_mul_f32 v[40:41], v[40:41], v[20:21] op_sel_hi:[1,0]
	v_pk_mul_f32 v[38:39], v[38:39], v[20:21] op_sel_hi:[1,0]
	v_pk_mul_f32 v[36:37], v[36:37], v[20:21] op_sel_hi:[1,0]
	v_pk_mul_f32 v[34:35], v[34:35], v[20:21] op_sel_hi:[1,0]
	v_pk_mul_f32 v[16:17], v[16:17], v[20:21] op_sel_hi:[1,0]
	v_pk_mul_f32 v[14:15], v[14:15], v[20:21] op_sel_hi:[1,0]
	v_pk_mul_f32 v[12:13], v[12:13], v[20:21] op_sel_hi:[1,0]
	v_pk_mul_f32 v[10:11], v[10:11], v[20:21] op_sel_hi:[1,0]
	v_pk_mul_f32 v[8:9], v[8:9], v[20:21] op_sel_hi:[1,0]
	v_pk_mul_f32 v[6:7], v[6:7], v[20:21] op_sel_hi:[1,0]
	v_pk_mul_f32 v[4:5], v[4:5], v[20:21] op_sel_hi:[1,0]
	v_pk_mul_f32 v[2:3], v[2:3], v[20:21] op_sel_hi:[1,0]
	v_mov_b32_e32 v19, v18
	v_mov_b32_e32 v20, v18
	v_mov_b32_e32 v21, v18
	v_mov_b32_e32 v22, v18
	v_mov_b32_e32 v23, v18
	v_mov_b32_e32 v24, v18
	v_mov_b32_e32 v25, v18
	v_mov_b32_e32 v26, v18
	v_mov_b32_e32 v27, v18
	v_mov_b32_e32 v28, v18
	v_mov_b32_e32 v29, v18
	v_mov_b32_e32 v30, v18
	v_mov_b32_e32 v31, v18
	v_mov_b32_e32 v32, v18
	v_mov_b32_e32 v33, v18
.LBB0_855:
	v_exp_f32_e32 v131, v66
	v_exp_f32_e32 v138, v50
	v_exp_f32_e32 v0, v67
	v_exp_f32_e32 v116, v51
	v_exp_f32_e32 v139, v68
	v_add_f32_e32 v117, v138, v131
	v_exp_f32_e32 v140, v52
	v_pk_add_f32 v[50:51], v[116:117], v[0:1]
	v_exp_f32_e32 v66, v55
	v_pk_add_f32 v[132:133], v[50:51], v[50:51] op_sel_hi:[0,1]
	v_exp_f32_e32 v132, v69
	v_exp_f32_e32 v50, v53
	v_add_f32_e32 v51, v140, v139
	v_exp_f32_e32 v68, v57
	v_exp_f32_e32 v141, v58
	v_pk_add_f32 v[52:53], v[50:51], v[132:133]
	v_exp_f32_e32 v51, v70
	v_pk_add_f32 v[134:135], v[52:53], v[52:53] op_sel_hi:[0,1]
	v_exp_f32_e32 v133, v54
	v_exp_f32_e32 v134, v71
	v_add_u32_e32 v117, 0x1c800, v130
	v_add_f32_e32 v67, v133, v51
	v_pk_add_f32 v[52:53], v[66:67], v[134:135]
	v_exp_f32_e32 v67, v72
	v_pk_add_f32 v[70:71], v[52:53], v[52:53] op_sel_hi:[0,1]
	v_exp_f32_e32 v135, v56
	v_exp_f32_e32 v70, v73
	v_add_f32_e32 v69, v135, v67
	v_pk_add_f32 v[52:53], v[68:69], v[70:71]
	v_exp_f32_e32 v69, v74
	v_pk_add_f32 v[136:137], v[52:53], v[52:53] op_sel_hi:[0,1]
	v_exp_f32_e32 v136, v75
	v_exp_f32_e32 v52, v59
	v_add_f32_e32 v53, v141, v69
	v_pk_add_f32 v[54:55], v[52:53], v[136:137]
	s_nop 0
	v_pk_add_f32 v[74:75], v[54:55], v[54:55] op_sel_hi:[0,1]
	v_exp_f32_e32 v53, v76
	v_exp_f32_e32 v137, v60
	v_exp_f32_e32 v74, v77
	v_exp_f32_e32 v54, v61
	v_add_f32_e32 v55, v137, v53
	v_pk_add_f32 v[56:57], v[54:55], v[74:75]
	s_nop 0
	v_pk_add_f32 v[76:77], v[56:57], v[56:57] op_sel_hi:[0,1]
	v_exp_f32_e32 v55, v78
	v_exp_f32_e32 v75, v62
	v_exp_f32_e32 v76, v79
	v_exp_f32_e32 v56, v63
	v_add_f32_e32 v57, v75, v55
	v_pk_add_f32 v[58:59], v[56:57], v[76:77]
	s_nop 0
	v_pk_add_f32 v[78:79], v[58:59], v[58:59] op_sel_hi:[0,1]
	v_exp_f32_e32 v57, v80
	v_exp_f32_e32 v77, v64
	v_exp_f32_e32 v78, v81
	v_exp_f32_e32 v58, v65
	v_add_f32_e32 v59, v77, v57
	v_pk_add_f32 v[60:61], v[58:59], v[78:79]
	s_nop 0
	v_pk_add_f32 v[60:61], v[60:61], v[60:61] op_sel:[0,1] op_sel_hi:[1,0]
	s_nop 0
	v_mov_b32_e32 v59, v60
	s_nop 1
	v_permlane32_swap_b32_e32 v60, v59
	v_add_f32_e32 v59, v60, v59
	v_cvt_pk_bf16_f32 v60, v131, v0
	v_cvt_pk_bf16_f32 v61, v139, v132
	v_cvt_pk_bf16_f32 v62, v51, v134
	v_cvt_pk_bf16_f32 v63, v67, v70
	ds_read_b64_tr_b16 v[70:71], v117
	ds_read_b64_tr_b16 v[72:73], v117 offset:1152
	s_waitcnt lgkmcnt(0)
	v_mfma_f32_32x32x16_bf16 v[34:49], v[70:73], v[60:63], v[34:49]
	ds_read_b64_tr_b16 v[70:71], v117 offset:64
	ds_read_b64_tr_b16 v[72:73], v117 offset:1216
	v_add_f32_e32 v129, v129, v59
	s_waitcnt lgkmcnt(0)
	v_mfma_f32_32x32x16_bf16 v[2:17], v[70:73], v[60:63], v[2:17]
	v_cvt_pk_bf16_f32 v60, v69, v136
	v_cvt_pk_bf16_f32 v61, v53, v74
	v_cvt_pk_bf16_f32 v62, v55, v76
	v_cvt_pk_bf16_f32 v63, v57, v78
	ds_read_b64_tr_b16 v[70:71], v117 offset:2304
	ds_read_b64_tr_b16 v[72:73], v117 offset:3456
	s_waitcnt lgkmcnt(0)
	v_mfma_f32_32x32x16_bf16 v[34:49], v[70:73], v[60:63], v[34:49]
	ds_read_b64_tr_b16 v[70:71], v117 offset:2368
	ds_read_b64_tr_b16 v[72:73], v117 offset:3520
	s_waitcnt lgkmcnt(0)
	v_mfma_f32_32x32x16_bf16 v[2:17], v[70:73], v[60:63], v[2:17]
	v_cvt_pk_bf16_f32 v60, v138, v116
	v_cvt_pk_bf16_f32 v61, v140, v50
	v_cvt_pk_bf16_f32 v62, v133, v66
	v_cvt_pk_bf16_f32 v63, v135, v68
	ds_read_b64_tr_b16 v[64:65], v117 offset:4608
	ds_read_b64_tr_b16 v[66:67], v117 offset:5760
	s_waitcnt lgkmcnt(0)
	v_mfma_f32_32x32x16_bf16 v[34:49], v[64:67], v[60:63], v[34:49]
	ds_read_b64_tr_b16 v[64:65], v117 offset:4672
	ds_read_b64_tr_b16 v[66:67], v117 offset:5824
	v_cvt_pk_bf16_f32 v50, v141, v52
	v_cvt_pk_bf16_f32 v51, v137, v54
	v_cvt_pk_bf16_f32 v52, v75, v56
	v_cvt_pk_bf16_f32 v53, v77, v58
	ds_read_b64_tr_b16 v[54:55], v117 offset:6912
	ds_read_b64_tr_b16 v[56:57], v117 offset:8064
	s_waitcnt lgkmcnt(2)
	v_mfma_f32_32x32x16_bf16 v[2:17], v[64:67], v[60:63], v[2:17]
	s_waitcnt lgkmcnt(0)
	v_mfma_f32_32x32x16_bf16 v[34:49], v[54:57], v[50:53], v[34:49]
	ds_read_b64_tr_b16 v[54:55], v117 offset:6976
	ds_read_b64_tr_b16 v[56:57], v117 offset:8128
	s_waitcnt vmcnt(3)
	ds_write_b128 v124, v[106:109]
	s_waitcnt vmcnt(2)
	ds_write_b128 v125, v[110:113]
	s_waitcnt lgkmcnt(0)
	s_barrier
	ds_read_b128 v[106:109], v127
	ds_read_b128 v[110:113], v127 offset:16
	ds_read_b128 v[130:133], v127 offset:32
	ds_read_b128 v[134:137], v127 offset:48
	ds_read_b128 v[66:69], v123
	ds_read_b128 v[70:73], v123 offset:16
	ds_read_b128 v[74:77], v123 offset:32
	ds_read_b128 v[78:81], v123 offset:48
	v_mfma_f32_32x32x16_bf16 v[2:17], v[54:57], v[50:53], v[2:17]
	s_waitcnt lgkmcnt(3)
	v_mfma_f32_32x32x16_bf16 v[50:65], v[66:69], v[90:93], v[18:33]
	s_waitcnt lgkmcnt(2)
	v_mfma_f32_32x32x16_bf16 v[50:65], v[70:73], v[86:89], v[50:65]
	s_waitcnt lgkmcnt(1)
	v_mfma_f32_32x32x16_bf16 v[50:65], v[74:77], v[82:85], v[50:65]
	s_waitcnt lgkmcnt(0)
	v_mfma_f32_32x32x16_bf16 v[50:65], v[78:81], v[94:97], v[50:65]
	v_mfma_f32_32x32x16_bf16 v[66:81], v[106:109], v[90:93], v[18:33]
	s_nop 10
	v_max_f32_e32 v0, v51, v51
	v_mfma_f32_32x32x16_bf16 v[66:81], v[110:113], v[86:89], v[66:81]
	v_mfma_f32_32x32x16_bf16 v[66:81], v[130:133], v[82:85], v[66:81]
	v_mfma_f32_32x32x16_bf16 v[66:81], v[134:137], v[94:97], v[66:81]
	s_nop 11
	v_max3_f32 v0, v67, v0, v52
	v_max3_f32 v106, v58, v74, v59
	v_max3_f32 v0, v0, v68, v53
	v_max3_f32 v106, v106, v75, v60
	v_max3_f32 v0, v0, v69, v66
	v_max3_f32 v106, v106, v76, v61
	v_max3_f32 v0, v0, v50, v54
	v_max3_f32 v106, v106, v77, v62
	v_max3_f32 v0, v0, v70, v55
	v_max3_f32 v106, v106, v78, v63
	v_max3_f32 v0, v0, v71, v56
	v_max3_f32 v106, v106, v79, v64
	v_max3_f32 v0, v0, v72, v57
	v_max3_f32 v106, v106, v80, v65
	v_max3_f32 v0, v0, v73, v73
	v_max3_f32 v106, v106, v81, v81
	v_max_f32_e32 v0, v0, v106
	v_mov_b32_e32 v106, v0
	s_nop 1
	v_permlane32_swap_b32_e32 v0, v106
	v_max_f32_e32 v106, v106, v106
	v_max_f32_e32 v0, v0, v0
	v_max_f32_e32 v0, v0, v106
	v_cmp_lt_f32_e32 vcc, s57, v0
	s_cbranch_vccz .LBB0_857
	v_max_f32_e32 v0, v0, v0
	v_max_f32_e32 v0, 0, v0
	v_exp_f32_e64 v20, -v0
	v_add_f32_e32 v18, v126, v0
	v_xor_b32_e32 v18, 0x80000000, v18
	v_pk_add_f32 v[66:67], v[66:67], v[0:1] op_sel_hi:[1,0] neg_lo:[0,1] neg_hi:[0,1]
	v_mul_f32_e32 v129, v129, v20
	v_pk_add_f32 v[50:51], v[50:51], v[0:1] op_sel_hi:[1,0] neg_lo:[0,1] neg_hi:[0,1]
	v_pk_add_f32 v[68:69], v[68:69], v[0:1] op_sel_hi:[1,0] neg_lo:[0,1] neg_hi:[0,1]
	v_pk_add_f32 v[52:53], v[52:53], v[0:1] op_sel_hi:[1,0] neg_lo:[0,1] neg_hi:[0,1]
	v_pk_add_f32 v[70:71], v[70:71], v[0:1] op_sel_hi:[1,0] neg_lo:[0,1] neg_hi:[0,1]
	v_pk_add_f32 v[54:55], v[54:55], v[0:1] op_sel_hi:[1,0] neg_lo:[0,1] neg_hi:[0,1]
	v_pk_add_f32 v[72:73], v[72:73], v[0:1] op_sel_hi:[1,0] neg_lo:[0,1] neg_hi:[0,1]
	v_pk_add_f32 v[56:57], v[56:57], v[0:1] op_sel_hi:[1,0] neg_lo:[0,1] neg_hi:[0,1]
	v_pk_add_f32 v[74:75], v[74:75], v[0:1] op_sel_hi:[1,0] neg_lo:[0,1] neg_hi:[0,1]
	v_pk_add_f32 v[58:59], v[58:59], v[0:1] op_sel_hi:[1,0] neg_lo:[0,1] neg_hi:[0,1]
	v_pk_add_f32 v[76:77], v[76:77], v[0:1] op_sel_hi:[1,0] neg_lo:[0,1] neg_hi:[0,1]
	v_pk_add_f32 v[60:61], v[60:61], v[0:1] op_sel_hi:[1,0] neg_lo:[0,1] neg_hi:[0,1]
	v_pk_add_f32 v[78:79], v[78:79], v[0:1] op_sel_hi:[1,0] neg_lo:[0,1] neg_hi:[0,1]
	v_pk_add_f32 v[62:63], v[62:63], v[0:1] op_sel_hi:[1,0] neg_lo:[0,1] neg_hi:[0,1]
	v_pk_add_f32 v[80:81], v[80:81], v[0:1] op_sel_hi:[1,0] neg_lo:[0,1] neg_hi:[0,1]
	v_pk_add_f32 v[64:65], v[64:65], v[0:1] op_sel_hi:[1,0] neg_lo:[0,1] neg_hi:[0,1]
	v_pk_mul_f32 v[48:49], v[48:49], v[20:21] op_sel_hi:[1,0]
	v_pk_mul_f32 v[46:47], v[46:47], v[20:21] op_sel_hi:[1,0]
	v_pk_mul_f32 v[44:45], v[44:45], v[20:21] op_sel_hi:[1,0]
	v_pk_mul_f32 v[42:43], v[42:43], v[20:21] op_sel_hi:[1,0]
	v_pk_mul_f32 v[40:41], v[40:41], v[20:21] op_sel_hi:[1,0]
	v_pk_mul_f32 v[38:39], v[38:39], v[20:21] op_sel_hi:[1,0]
	v_pk_mul_f32 v[36:37], v[36:37], v[20:21] op_sel_hi:[1,0]
	v_pk_mul_f32 v[34:35], v[34:35], v[20:21] op_sel_hi:[1,0]
	v_pk_mul_f32 v[16:17], v[16:17], v[20:21] op_sel_hi:[1,0]
	v_pk_mul_f32 v[14:15], v[14:15], v[20:21] op_sel_hi:[1,0]
	v_pk_mul_f32 v[12:13], v[12:13], v[20:21] op_sel_hi:[1,0]
	v_pk_mul_f32 v[10:11], v[10:11], v[20:21] op_sel_hi:[1,0]
	v_pk_mul_f32 v[8:9], v[8:9], v[20:21] op_sel_hi:[1,0]
	v_pk_mul_f32 v[6:7], v[6:7], v[20:21] op_sel_hi:[1,0]
	v_pk_mul_f32 v[4:5], v[4:5], v[20:21] op_sel_hi:[1,0]
	v_pk_mul_f32 v[2:3], v[2:3], v[20:21] op_sel_hi:[1,0]
	v_mov_b32_e32 v19, v18
	v_mov_b32_e32 v20, v18
	v_mov_b32_e32 v21, v18
	v_mov_b32_e32 v22, v18
	v_mov_b32_e32 v23, v18
	v_mov_b32_e32 v24, v18
	v_mov_b32_e32 v25, v18
	v_mov_b32_e32 v26, v18
	v_mov_b32_e32 v27, v18
	v_mov_b32_e32 v28, v18
	v_mov_b32_e32 v29, v18
	v_mov_b32_e32 v30, v18
	v_mov_b32_e32 v31, v18
	v_mov_b32_e32 v32, v18
	v_mov_b32_e32 v33, v18
.LBB0_857:
	v_exp_f32_e32 v116, v66
	v_exp_f32_e32 v123, v50
	v_exp_f32_e32 v0, v67
	v_exp_f32_e32 v106, v51
	v_exp_f32_e32 v124, v52
	v_add_f32_e32 v107, v123, v116
	v_exp_f32_e32 v66, v55
	v_pk_add_f32 v[50:51], v[106:107], v[0:1]
	v_exp_f32_e32 v107, v68
	v_pk_add_f32 v[108:109], v[50:51], v[50:51] op_sel_hi:[0,1]
	v_exp_f32_e32 v108, v69
	v_exp_f32_e32 v50, v53
	v_add_f32_e32 v51, v124, v107
	v_exp_f32_e32 v72, v72
	v_exp_f32_e32 v68, v57
	v_pk_add_f32 v[52:53], v[50:51], v[108:109]
	v_exp_f32_e32 v51, v70
	v_pk_add_f32 v[110:111], v[52:53], v[52:53] op_sel_hi:[0,1]
	v_exp_f32_e32 v109, v54
	v_exp_f32_e32 v110, v71
	v_exp_f32_e32 v125, v58
	v_exp_f32_e32 v64, v64
	v_add_f32_e32 v67, v109, v51
	v_pk_add_f32 v[52:53], v[66:67], v[110:111]
	v_exp_f32_e32 v111, v56
	v_pk_add_f32 v[70:71], v[52:53], v[52:53] op_sel_hi:[0,1]
	v_exp_f32_e32 v70, v73
	v_add_f32_e32 v69, v111, v72
	v_pk_add_f32 v[52:53], v[68:69], v[70:71]
	s_nop 0
	v_pk_add_f32 v[112:113], v[52:53], v[52:53] op_sel_hi:[0,1]
	v_exp_f32_e32 v69, v74
	v_exp_f32_e32 v112, v75
	v_exp_f32_e32 v52, v59
	v_add_f32_e32 v53, v125, v69
	v_pk_add_f32 v[54:55], v[52:53], v[112:113]
	s_nop 0
	v_pk_add_f32 v[74:75], v[54:55], v[54:55] op_sel_hi:[0,1]
	v_exp_f32_e32 v53, v76
	v_exp_f32_e32 v113, v60
	v_exp_f32_e32 v74, v77
	v_exp_f32_e32 v54, v61
	v_add_f32_e32 v55, v113, v53
	v_pk_add_f32 v[56:57], v[54:55], v[74:75]
	s_nop 0
	v_pk_add_f32 v[76:77], v[56:57], v[56:57] op_sel_hi:[0,1]
	v_exp_f32_e32 v55, v78
	v_exp_f32_e32 v75, v62
	v_exp_f32_e32 v76, v79
	v_exp_f32_e32 v56, v63
	v_add_f32_e32 v57, v75, v55
	v_pk_add_f32 v[58:59], v[56:57], v[76:77]
	s_nop 0
	v_pk_add_f32 v[78:79], v[58:59], v[58:59] op_sel_hi:[0,1]
	v_exp_f32_e32 v57, v80
	v_exp_f32_e32 v78, v81
	v_exp_f32_e32 v58, v65
	v_add_f32_e32 v59, v64, v57
	v_pk_add_f32 v[60:61], v[58:59], v[78:79]
	s_nop 0
	v_pk_add_f32 v[60:61], v[60:61], v[60:61] op_sel:[0,1] op_sel_hi:[1,0]
	s_nop 0
	v_mov_b32_e32 v59, v60
	s_nop 1
	v_permlane32_swap_b32_e32 v60, v59
	v_add_f32_e32 v59, v60, v59
	v_cvt_pk_bf16_f32 v60, v116, v0
	v_cvt_pk_bf16_f32 v61, v107, v108
	v_cvt_pk_bf16_f32 v62, v51, v110
	v_cvt_pk_bf16_f32 v63, v72, v70
	ds_read_b64_tr_b16 v[70:71], v115
	ds_read_b64_tr_b16 v[72:73], v115 offset:1152
	s_waitcnt lgkmcnt(0)
	v_mfma_f32_32x32x16_bf16 v[34:49], v[70:73], v[60:63], v[34:49]
	ds_read_b64_tr_b16 v[70:71], v115 offset:64
	ds_read_b64_tr_b16 v[72:73], v115 offset:1216
	v_add_f32_e32 v67, v129, v59
	s_waitcnt lgkmcnt(0)
	v_mfma_f32_32x32x16_bf16 v[2:17], v[70:73], v[60:63], v[2:17]
	v_cvt_pk_bf16_f32 v60, v69, v112
	v_cvt_pk_bf16_f32 v61, v53, v74
	v_cvt_pk_bf16_f32 v62, v55, v76
	v_cvt_pk_bf16_f32 v63, v57, v78
	ds_read_b64_tr_b16 v[70:71], v115 offset:2304
	ds_read_b64_tr_b16 v[72:73], v115 offset:3456
	s_waitcnt lgkmcnt(0)
	v_mfma_f32_32x32x16_bf16 v[34:49], v[70:73], v[60:63], v[34:49]
	ds_read_b64_tr_b16 v[70:71], v115 offset:2368
	ds_read_b64_tr_b16 v[72:73], v115 offset:3520
	s_waitcnt lgkmcnt(0)
	v_mfma_f32_32x32x16_bf16 v[2:17], v[70:73], v[60:63], v[2:17]
	v_cvt_pk_bf16_f32 v60, v123, v106
	v_cvt_pk_bf16_f32 v61, v124, v50
	v_cvt_pk_bf16_f32 v62, v109, v66
	v_cvt_pk_bf16_f32 v63, v111, v68
	ds_read_b64_tr_b16 v[68:69], v115 offset:4608
	ds_read_b64_tr_b16 v[70:71], v115 offset:5760
	s_waitcnt lgkmcnt(0)
	v_mfma_f32_32x32x16_bf16 v[34:49], v[68:71], v[60:63], v[34:49]
	ds_read_b64_tr_b16 v[68:69], v115 offset:4672
	ds_read_b64_tr_b16 v[70:71], v115 offset:5824
	v_cvt_pk_bf16_f32 v50, v125, v52
	v_cvt_pk_bf16_f32 v51, v113, v54
	v_cvt_pk_bf16_f32 v52, v75, v56
	v_cvt_pk_bf16_f32 v53, v64, v58
	ds_read_b64_tr_b16 v[54:55], v115 offset:6912
	ds_read_b64_tr_b16 v[56:57], v115 offset:8064
	s_waitcnt lgkmcnt(2)
	v_mfma_f32_32x32x16_bf16 v[2:17], v[68:71], v[60:63], v[2:17]
	s_waitcnt lgkmcnt(0)
	v_mfma_f32_32x32x16_bf16 v[34:49], v[54:57], v[50:53], v[34:49]
	ds_read_b64_tr_b16 v[54:55], v115 offset:6976
	ds_read_b64_tr_b16 v[56:57], v115 offset:8128
	s_waitcnt vmcnt(1)
	ds_write_b128 v120, v[98:101]
	s_waitcnt vmcnt(0)
	ds_write_b128 v121, v[102:105]
	s_waitcnt lgkmcnt(0)
	s_barrier
	ds_read_b128 v[68:71], v122
	ds_read_b128 v[72:75], v122 offset:16
	ds_read_b128 v[76:79], v122 offset:32
	ds_read_b128 v[98:101], v122 offset:48
	ds_read_b128 v[102:105], v119
	ds_read_b128 v[106:109], v119 offset:16
	ds_read_b128 v[110:113], v119 offset:32
	ds_read_b128 v[120:123], v119 offset:48
	v_mfma_f32_32x32x16_bf16 v[2:17], v[54:57], v[50:53], v[2:17]
	s_waitcnt lgkmcnt(3)
	v_mfma_f32_32x32x16_bf16 v[50:65], v[102:105], v[90:93], v[18:33]
	v_mfma_f32_32x32x16_bf16 v[18:33], v[68:71], v[90:93], v[18:33]
	s_waitcnt lgkmcnt(2)
	v_mfma_f32_32x32x16_bf16 v[50:65], v[106:109], v[86:89], v[50:65]
	v_mfma_f32_32x32x16_bf16 v[18:33], v[72:75], v[86:89], v[18:33]
	s_waitcnt lgkmcnt(1)
	v_mfma_f32_32x32x16_bf16 v[50:65], v[110:113], v[82:85], v[50:65]
	v_mfma_f32_32x32x16_bf16 v[18:33], v[76:79], v[82:85], v[18:33]
	s_waitcnt lgkmcnt(0)
	v_mfma_f32_32x32x16_bf16 v[50:65], v[120:123], v[94:97], v[50:65]
	v_mfma_f32_32x32x16_bf16 v[18:33], v[98:101], v[94:97], v[18:33]
	s_nop 10
	v_max3_f32 v0, v51, v19, v52
	v_max3_f32 v66, v58, v26, v59
	v_max3_f32 v0, v0, v20, v53
	v_max3_f32 v66, v66, v27, v60
	v_max3_f32 v0, v0, v21, v18
	v_max3_f32 v66, v66, v28, v61
	v_max3_f32 v0, v0, v50, v54
	v_max3_f32 v66, v66, v29, v62
	v_max3_f32 v0, v0, v22, v55
	v_max3_f32 v66, v66, v30, v63
	v_max3_f32 v0, v0, v23, v56
	v_max3_f32 v66, v66, v31, v64
	v_max3_f32 v0, v0, v24, v57
	v_max3_f32 v66, v66, v32, v65
	v_max3_f32 v0, v0, v25, v25
	v_max3_f32 v66, v66, v33, v33
	v_max_f32_e32 v0, v0, v66
	v_mov_b32_e32 v66, v0
	s_nop 1
	v_permlane32_swap_b32_e32 v0, v66
	v_max_f32_e32 v66, v66, v66
	v_max_f32_e32 v0, v0, v0
	v_max_f32_e32 v0, v0, v66
	v_cmp_lt_f32_e32 vcc, s57, v0
	s_cbranch_vccz .LBB0_859
	v_max_f32_e32 v0, v0, v0
	v_max_f32_e32 v0, 0, v0
	v_exp_f32_e64 v66, -v0
	v_pk_add_f32 v[18:19], v[18:19], v[0:1] op_sel_hi:[1,0] neg_lo:[0,1] neg_hi:[0,1]
	v_pk_add_f32 v[50:51], v[50:51], v[0:1] op_sel_hi:[1,0] neg_lo:[0,1] neg_hi:[0,1]
	v_pk_add_f32 v[20:21], v[20:21], v[0:1] op_sel_hi:[1,0] neg_lo:[0,1] neg_hi:[0,1]
	v_mul_f32_e32 v67, v67, v66
	v_pk_add_f32 v[52:53], v[52:53], v[0:1] op_sel_hi:[1,0] neg_lo:[0,1] neg_hi:[0,1]
	v_pk_add_f32 v[22:23], v[22:23], v[0:1] op_sel_hi:[1,0] neg_lo:[0,1] neg_hi:[0,1]
	v_pk_add_f32 v[54:55], v[54:55], v[0:1] op_sel_hi:[1,0] neg_lo:[0,1] neg_hi:[0,1]
	v_pk_add_f32 v[24:25], v[24:25], v[0:1] op_sel_hi:[1,0] neg_lo:[0,1] neg_hi:[0,1]
	v_pk_add_f32 v[56:57], v[56:57], v[0:1] op_sel_hi:[1,0] neg_lo:[0,1] neg_hi:[0,1]
	v_pk_add_f32 v[26:27], v[26:27], v[0:1] op_sel_hi:[1,0] neg_lo:[0,1] neg_hi:[0,1]
	v_pk_add_f32 v[58:59], v[58:59], v[0:1] op_sel_hi:[1,0] neg_lo:[0,1] neg_hi:[0,1]
	v_pk_add_f32 v[28:29], v[28:29], v[0:1] op_sel_hi:[1,0] neg_lo:[0,1] neg_hi:[0,1]
	v_pk_add_f32 v[60:61], v[60:61], v[0:1] op_sel_hi:[1,0] neg_lo:[0,1] neg_hi:[0,1]
	v_pk_add_f32 v[30:31], v[30:31], v[0:1] op_sel_hi:[1,0] neg_lo:[0,1] neg_hi:[0,1]
	v_pk_add_f32 v[62:63], v[62:63], v[0:1] op_sel_hi:[1,0] neg_lo:[0,1] neg_hi:[0,1]
	v_pk_add_f32 v[32:33], v[32:33], v[0:1] op_sel_hi:[1,0] neg_lo:[0,1] neg_hi:[0,1]
	v_pk_add_f32 v[64:65], v[64:65], v[0:1] op_sel_hi:[1,0] neg_lo:[0,1] neg_hi:[0,1]
	v_pk_mul_f32 v[48:49], v[48:49], v[66:67] op_sel_hi:[1,0]
	v_pk_mul_f32 v[46:47], v[46:47], v[66:67] op_sel_hi:[1,0]
	v_pk_mul_f32 v[44:45], v[44:45], v[66:67] op_sel_hi:[1,0]
	v_pk_mul_f32 v[42:43], v[42:43], v[66:67] op_sel_hi:[1,0]
	v_pk_mul_f32 v[40:41], v[40:41], v[66:67] op_sel_hi:[1,0]
	v_pk_mul_f32 v[38:39], v[38:39], v[66:67] op_sel_hi:[1,0]
	v_pk_mul_f32 v[36:37], v[36:37], v[66:67] op_sel_hi:[1,0]
	v_pk_mul_f32 v[34:35], v[34:35], v[66:67] op_sel_hi:[1,0]
	v_pk_mul_f32 v[16:17], v[16:17], v[66:67] op_sel_hi:[1,0]
	v_pk_mul_f32 v[14:15], v[14:15], v[66:67] op_sel_hi:[1,0]
	v_pk_mul_f32 v[12:13], v[12:13], v[66:67] op_sel_hi:[1,0]
	v_pk_mul_f32 v[10:11], v[10:11], v[66:67] op_sel_hi:[1,0]
	v_pk_mul_f32 v[8:9], v[8:9], v[66:67] op_sel_hi:[1,0]
	v_pk_mul_f32 v[6:7], v[6:7], v[66:67] op_sel_hi:[1,0]
	v_pk_mul_f32 v[4:5], v[4:5], v[66:67] op_sel_hi:[1,0]
	v_pk_mul_f32 v[2:3], v[2:3], v[66:67] op_sel_hi:[1,0]

.LBB0_860:
	s_and_b64 vcc, exec, s[6:7]
	s_cbranch_vccz .LBB0_848
	s_and_b32 s62, s68, 0xffffffc0
	v_mbcnt_lo_u32_b32 v114, -1, 0
	v_mbcnt_hi_u32_b32 v114, -1, v114
	s_and_b32 s2, s68, 7
	v_or_b32_e32 v0, v114, v128
	v_and_b32_e32 v17, 7, v114
	s_add_i32 s6, s62, 0x800
	v_ashrrev_i32_e32 v16, 3, v0
	v_lshlrev_b32_e32 v124, 3, v17
	v_lshl_add_u32 v0, s2, 8, v16
	v_or_b32_e32 v62, s6, v124
	v_mov_b64_e32 v[10:11], s[80:81]
	s_ashr_i32 s63, s62, 31
	v_add_u32_e32 v0, 0x4000, v0
	v_ashrrev_i32_e32 v63, 31, v62
	v_mad_i64_i32 v[60:61], s[8:9], v0, s44, v[10:11]
	v_or_b32_e32 v2, s62, v124
	v_mov_b32_e32 v3, s63
	v_lshlrev_b64 v[12:13], 1, v[62:63]
	v_lshl_add_u64 v[2:3], v[2:3], 1, v[60:61]
	v_lshl_add_u64 v[6:7], v[60:61], 0, v[12:13]
	global_load_dwordx4 v[2:5], v[2:3], off offset:2048
	s_nop 0
	global_load_dwordx4 v[6:9], v[6:7], off
	s_lshr_b32 s4, s68, 1
	s_and_b32 s5, s4, 28
	v_readlane_b32 s4, v254, 19
	s_add_i32 s5, s5, s4
	v_bfe_u32 v117, v114, 4, 1
	v_and_b32_e32 v120, 15, v114
	v_readlane_b32 s4, v254, 20
	v_or_b32_e32 v0, s5, v117
	v_and_b32_e32 v14, 0xffffffe0, v114
	v_or_b32_e32 v121, s4, v120
	s_lshl_b32 s4, s2, 11
	v_lshl_add_u32 v0, v0, 6, s4
	v_or_b32_e32 v0, v0, v121
	v_mad_u64_u32 v[10:11], s[8:9], v0, s44, v[10:11]
	v_lshl_add_u64 v[10:11], s[62:63], 1, v[10:11]
	v_ashrrev_i32_e32 v15, 31, v14
	v_lshl_add_u64 v[10:11], v[14:15], 1, v[10:11]
	global_load_dwordx4 v[82:85], v[10:11], off
	global_load_dwordx4 v[86:89], v[10:11], off offset:16
	global_load_dwordx4 v[90:93], v[10:11], off offset:32
	s_add_i32 s64, s62, 0x400
	v_lshlrev_b32_e32 v116, 4, v17
	s_movk_i32 s7, 0x90
	v_lshlrev_b32_e32 v14, 1, v114
	s_waitcnt vmcnt(15)
	v_mad_u64_u32 v[66:67], s[8:9], v16, s7, v[116:117]
	v_or_b32_e32 v64, s64, v124
	v_and_b32_e32 v122, 31, v114
	v_and_b32_e32 v14, 0xffffffc0, v14
	v_ashrrev_i32_e32 v65, 31, v64
	s_mov_b64 s[8:9], 0x60000
	v_mad_u32_u24 v67, v122, s7, v14
	v_lshlrev_b64 v[14:15], 1, v[64:65]
	v_lshl_add_u64 v[16:17], v[60:61], 0, s[8:9]
	v_lshl_add_u64 v[20:21], v[16:17], 0, v[14:15]
	v_lshl_add_u64 v[16:17], v[16:17], 0, v[12:13]
	global_load_dwordx4 v[56:59], v[20:21], off
	global_load_dwordx4 v[52:55], v[16:17], off
	global_load_dwordx4 v[94:97], v[10:11], off offset:48
	s_mov_b64 s[8:9], 0xc0000
	s_add_i32 s2, 0, 0x18000
	v_add_u32_e32 v68, 0, v67
	v_lshl_add_u64 v[18:19], v[60:61], 0, s[8:9]
	v_add_u32_e32 v136, s2, v66
	v_add_u32_e32 v69, 0, v66
	v_add_u32_e32 v135, 0x19200, v68
	v_lshl_add_u64 v[14:15], v[18:19], 0, v[14:15]
	v_add_u32_e32 v137, 0x1a400, v69
	v_lshl_add_u64 v[12:13], v[18:19], 0, v[12:13]
	s_waitcnt lgkmcnt(0)
	s_barrier
	global_load_dwordx4 v[106:109], v[14:15], off
	global_load_dwordx4 v[110:113], v[12:13], off
	v_add_u32_e32 v138, s2, v67
	s_movk_i32 s20, 0x90
	s_waitcnt vmcnt(9)
	ds_write_b128 v136, v[2:5]
	s_waitcnt vmcnt(8)
	ds_write_b128 v137, v[6:9]
	s_waitcnt lgkmcnt(0)
	s_barrier
	ds_read_b128 v[2:5], v135
	s_waitcnt vmcnt(7) lgkmcnt(0)
	v_mfma_f32_32x32x16_bf16 v[8:23], v[2:5], v[82:85], 0
	ds_read_b128 v[2:5], v138
	s_waitcnt lgkmcnt(0)
	v_mfma_f32_32x32x16_bf16 v[36:51], v[2:5], v[82:85], 0
	ds_read_b128 v[2:5], v135 offset:16
	s_waitcnt vmcnt(6) lgkmcnt(0)
	v_mfma_f32_32x32x16_bf16 v[8:23], v[2:5], v[86:89], v[8:23]
	ds_read_b128 v[2:5], v138 offset:16
	s_waitcnt lgkmcnt(0)
	v_mfma_f32_32x32x16_bf16 v[36:51], v[2:5], v[86:89], v[36:51]
	ds_read_b128 v[2:5], v135 offset:32
	s_waitcnt vmcnt(5) lgkmcnt(0)
	v_mfma_f32_32x32x16_bf16 v[8:23], v[2:5], v[90:93], v[8:23]
	ds_read_b128 v[2:5], v138 offset:32
	s_waitcnt lgkmcnt(0)
	v_mfma_f32_32x32x16_bf16 v[36:51], v[2:5], v[90:93], v[36:51]
	ds_read_b128 v[2:5], v135 offset:48
	s_waitcnt vmcnt(2) lgkmcnt(0)
	v_mfma_f32_32x32x16_bf16 v[8:23], v[2:5], v[94:97], v[8:23]
	ds_read_b128 v[2:5], v138 offset:48
	s_waitcnt lgkmcnt(0)
	v_mfma_f32_32x32x16_bf16 v[36:51], v[2:5], v[94:97], v[36:51]
	s_nop 8
	v_max3_f32 v2, v9, v10, v11
	v_max3_f32 v3, v16, v44, v17
	v_max3_f32 v2, v2, v12, v13
	v_max3_f32 v3, v3, v45, v18
	v_max3_f32 v2, v2, v14, v15
	v_max3_f32 v3, v3, v46, v19
	v_max3_f32 v2, v2, v37, v38
	v_max3_f32 v3, v3, v47, v20
	v_max3_f32 v2, v2, v39, v40
	v_max3_f32 v3, v3, v48, v21
	v_max3_f32 v2, v2, v41, v36
	v_max3_f32 v3, v3, v49, v22
	v_max3_f32 v2, v2, v8, v42
	v_max3_f32 v3, v3, v50, v23
	v_max3_f32 v2, v2, v43, v43
	v_max3_f32 v3, v3, v51, v51
	v_max_f32_e32 v2, v2, v3
	v_mov_b32_e32 v3, v2
	s_nop 1
	v_permlane32_swap_b32_e32 v2, v3
	v_max_f32_e32 v3, v3, v3
	v_max_f32_e32 v2, v2, v2
	v_max_f32_e32 v2, v2, v3
	v_cmp_lt_f32_e32 vcc, s57, v2
	s_cbranch_vccz .LBB0_863
	v_max_f32_e32 v2, v2, v2
	v_max_f32_e32 v4, 0, v2
	v_exp_f32_e64 v2, -v4
	v_add_f32_e32 v123, 0, v4
	v_xor_b32_e32 v34, 0x80000000, v123
	v_pk_add_f32 v[36:37], v[36:37], v[4:5] op_sel_hi:[1,0] neg_lo:[0,1] neg_hi:[0,1]
	v_mul_f32_e32 v2, 0, v2
	v_pk_add_f32 v[8:9], v[8:9], v[4:5] op_sel_hi:[1,0] neg_lo:[0,1] neg_hi:[0,1]
	v_pk_add_f32 v[38:39], v[38:39], v[4:5] op_sel_hi:[1,0] neg_lo:[0,1] neg_hi:[0,1]
	v_pk_add_f32 v[10:11], v[10:11], v[4:5] op_sel_hi:[1,0] neg_lo:[0,1] neg_hi:[0,1]
	v_pk_add_f32 v[40:41], v[40:41], v[4:5] op_sel_hi:[1,0] neg_lo:[0,1] neg_hi:[0,1]
	v_pk_add_f32 v[12:13], v[12:13], v[4:5] op_sel_hi:[1,0] neg_lo:[0,1] neg_hi:[0,1]
	v_pk_add_f32 v[42:43], v[42:43], v[4:5] op_sel_hi:[1,0] neg_lo:[0,1] neg_hi:[0,1]
	v_pk_add_f32 v[14:15], v[14:15], v[4:5] op_sel_hi:[1,0] neg_lo:[0,1] neg_hi:[0,1]
	v_pk_add_f32 v[44:45], v[44:45], v[4:5] op_sel_hi:[1,0] neg_lo:[0,1] neg_hi:[0,1]
	v_pk_add_f32 v[16:17], v[16:17], v[4:5] op_sel_hi:[1,0] neg_lo:[0,1] neg_hi:[0,1]
	v_pk_add_f32 v[46:47], v[46:47], v[4:5] op_sel_hi:[1,0] neg_lo:[0,1] neg_hi:[0,1]
	v_pk_add_f32 v[18:19], v[18:19], v[4:5] op_sel_hi:[1,0] neg_lo:[0,1] neg_hi:[0,1]
	v_pk_add_f32 v[48:49], v[48:49], v[4:5] op_sel_hi:[1,0] neg_lo:[0,1] neg_hi:[0,1]
	v_pk_add_f32 v[20:21], v[20:21], v[4:5] op_sel_hi:[1,0] neg_lo:[0,1] neg_hi:[0,1]
	v_pk_add_f32 v[50:51], v[50:51], v[4:5] op_sel_hi:[1,0] neg_lo:[0,1] neg_hi:[0,1]
	v_pk_add_f32 v[22:23], v[22:23], v[4:5] op_sel_hi:[1,0] neg_lo:[0,1] neg_hi:[0,1]
	s_branch .LBB0_864

.LBB0_864:
	v_exp_f32_e32 v33, v36
	v_exp_f32_e32 v35, v8
	v_exp_f32_e32 v24, v37
	v_exp_f32_e32 v70, v9
	v_mov_b32_e32 v25, v1
	v_add_f32_e32 v71, v35, v33
	v_exp_f32_e32 v72, v11
	v_pk_add_f32 v[8:9], v[70:71], v[24:25]
	v_exp_f32_e32 v25, v38
	v_pk_add_f32 v[26:27], v[8:9], v[8:9] op_sel_hi:[0,1]
	v_exp_f32_e32 v71, v10
	v_exp_f32_e32 v26, v39
	v_exp_f32_e32 v74, v13
	v_exp_f32_e32 v76, v15
	v_add_f32_e32 v73, v71, v25
	v_pk_add_f32 v[10:11], v[72:73], v[26:27]
	v_exp_f32_e32 v27, v40
	v_pk_add_f32 v[28:29], v[10:11], v[10:11] op_sel_hi:[0,1]
	v_exp_f32_e32 v73, v12
	v_exp_f32_e32 v28, v41
	v_exp_f32_e32 v130, v16
	v_exp_f32_e32 v80, v17
	v_add_f32_e32 v75, v73, v27
	v_pk_add_f32 v[12:13], v[74:75], v[28:29]
	v_exp_f32_e32 v29, v42
	v_pk_add_f32 v[30:31], v[12:13], v[12:13] op_sel_hi:[0,1]
	v_exp_f32_e32 v75, v14
	v_exp_f32_e32 v30, v43
	v_exp_f32_e32 v100, v19
	v_ashrrev_i32_e32 v126, 3, v114
	v_add_f32_e32 v77, v75, v29
	v_pk_add_f32 v[14:15], v[76:77], v[30:31]
	v_exp_f32_e32 v77, v44
	v_pk_add_f32 v[78:79], v[14:15], v[14:15] op_sel_hi:[0,1]
	v_exp_f32_e32 v78, v45
	v_bfe_u32 v3, v114, 2, 2
	v_add_f32_e32 v81, v130, v77
	s_mov_b32 s2, 0xffffffc
	v_pk_add_f32 v[16:17], v[80:81], v[78:79]
	v_exp_f32_e32 v79, v46
	v_pk_add_f32 v[98:99], v[16:17], v[16:17] op_sel_hi:[0,1]
	v_exp_f32_e32 v81, v18
	v_exp_f32_e32 v98, v47
	v_and_or_b32 v3, v126, s2, v3
	v_mul_lo_u32 v127, v3, s20
	v_add_f32_e32 v101, v81, v79
	v_pk_add_f32 v[18:19], v[100:101], v[98:99]
	v_and_b32_e32 v3, 16, v114
	v_lshlrev_b32_e32 v125, 2, v114
	v_pk_add_f32 v[102:103], v[18:19], v[18:19] op_sel_hi:[0,1]
	v_exp_f32_e32 v99, v48
	v_exp_f32_e32 v101, v20
	v_and_or_b32 v3, v125, 12, v3
	v_exp_f32_e32 v102, v49
	v_exp_f32_e32 v104, v21
	v_lshlrev_b32_e32 v134, 1, v3
	s_movk_i32 s2, 0x2400
	v_add3_u32 v32, v127, v134, s2
	v_add_u32_e32 v115, 0, v32
	v_add_f32_e32 v105, v101, v99
	v_add_u32_e32 v129, 0x18000, v115
	v_pk_add_f32 v[18:19], v[104:105], v[102:103]
	v_exp_f32_e32 v50, v50
	v_exp_f32_e32 v131, v22
	v_cvt_pk_bf16_f32 v36, v33, v24
	v_cvt_pk_bf16_f32 v37, v25, v26
	v_cvt_pk_bf16_f32 v38, v27, v28
	v_cvt_pk_bf16_f32 v39, v29, v30
	ds_read_b64_tr_b16 v[40:41], v129
	ds_read_b64_tr_b16 v[42:43], v129 offset:1152
	v_pk_add_f32 v[48:49], v[18:19], v[18:19] op_sel_hi:[0,1]
	v_exp_f32_e32 v48, v51
	v_exp_f32_e32 v118, v23
	v_mov_b32_e32 v3, v2
	v_mov_b32_e32 v4, v2
	v_mov_b32_e32 v5, v2
	v_mov_b32_e32 v6, v2
	v_mov_b32_e32 v7, v2
	v_mov_b32_e32 v8, v2
	v_mov_b32_e32 v9, v2
	v_mov_b32_e32 v10, v2
	v_mov_b32_e32 v11, v2
	v_mov_b32_e32 v12, v2
	v_mov_b32_e32 v13, v2
	v_mov_b32_e32 v14, v2
	v_mov_b32_e32 v15, v2
	v_mov_b32_e32 v16, v2
	v_mov_b32_e32 v17, v2
	v_add_f32_e32 v119, v131, v50
	ds_read_b64_tr_b16 v[46:47], v129 offset:1216
	ds_read_b64_tr_b16 v[44:45], v129 offset:64
	s_waitcnt lgkmcnt(2)
	v_mfma_f32_32x32x16_bf16 v[18:33], v[40:43], v[36:39], v[2:17]
	v_add_f32_e64 v40, v118, v48
	v_add_f32_e64 v41, v119, v49
	v_readlane_b32 s2, v254, 45
	v_pk_add_f32 v[40:41], v[40:41], v[40:41] op_sel:[0,1] op_sel_hi:[1,0]
	s_mov_b64 s[8:9], 0x120000
	v_mov_b32_e32 v41, v40
	s_nop 1
	v_permlane32_swap_b32_e32 v40, v41
	v_add_f32_e32 v40, v40, v41
	v_add_f32_e32 v139, v2, v40
	s_waitcnt lgkmcnt(0)
	v_mfma_f32_32x32x16_bf16 v[2:17], v[44:47], v[36:39], v[2:17]
	v_cvt_pk_bf16_f32 v36, v77, v78
	v_cvt_pk_bf16_f32 v37, v79, v98
	v_cvt_pk_bf16_f32 v38, v99, v102
	v_cvt_pk_bf16_f32 v39, v50, v48
	ds_read_b64_tr_b16 v[40:41], v129 offset:2304
	ds_read_b64_tr_b16 v[42:43], v129 offset:3456
	ds_read_b64_tr_b16 v[44:45], v129 offset:3520
	v_add_u32_e32 v132, 0x1ec00, v69
	v_add_u32_e32 v133, s2, v67
	s_waitcnt lgkmcnt(1)
	v_mfma_f32_32x32x16_bf16 v[18:33], v[40:43], v[36:39], v[18:33]
	ds_read_b64_tr_b16 v[42:43], v129 offset:2368
	s_waitcnt lgkmcnt(0)
	v_mfma_f32_32x32x16_bf16 v[2:17], v[42:45], v[36:39], v[2:17]
	v_cvt_pk_bf16_f32 v38, v35, v70
	v_cvt_pk_bf16_f32 v39, v71, v72
	v_cvt_pk_bf16_f32 v40, v73, v74
	v_cvt_pk_bf16_f32 v41, v75, v76
	ds_read_b64_tr_b16 v[42:43], v129 offset:4608
	ds_read_b64_tr_b16 v[44:45], v129 offset:5760
	ds_read_b64_tr_b16 v[48:49], v129 offset:5824
	ds_read_b64_tr_b16 v[46:47], v129 offset:4672
	v_cvt_pk_bf16_f32 v70, v130, v80
	s_waitcnt lgkmcnt(2)
	v_mfma_f32_32x32x16_bf16 v[18:33], v[42:45], v[38:41], v[18:33]
	v_cvt_pk_bf16_f32 v71, v81, v100
	v_cvt_pk_bf16_f32 v72, v101, v104
	v_cvt_pk_bf16_f32 v73, v131, v118
	ds_read_b64_tr_b16 v[74:75], v129 offset:6912
	ds_read_b64_tr_b16 v[76:77], v129 offset:8064
	v_add_u32_e32 v131, s2, v66
	v_add_u32_e32 v130, 0x1da00, v68
	v_mov_b32_e32 v35, v34
	s_waitcnt lgkmcnt(2)
	v_mfma_f32_32x32x16_bf16 v[2:17], v[46:49], v[38:41], v[2:17]
	v_lshl_add_u64 v[48:49], v[60:61], 0, s[8:9]
	ds_read_b64_tr_b16 v[46:47], v129 offset:8128
	ds_read_b64_tr_b16 v[44:45], v129 offset:6976
	ds_write_b128 v131, v[56:59]
	ds_write_b128 v132, v[52:55]
	v_lshl_add_u64 v[50:51], v[64:65], 1, v[48:49]
	v_lshl_add_u64 v[48:49], v[62:63], 1, v[48:49]
	global_load_dwordx4 v[98:101], v[50:51], off
	global_load_dwordx4 v[102:105], v[48:49], off
	s_waitcnt lgkmcnt(4)
	v_mfma_f32_32x32x16_bf16 v[18:33], v[74:77], v[70:73], v[18:33]
	s_waitcnt lgkmcnt(0)
	s_barrier
	ds_read_b128 v[74:77], v130
	v_mov_b32_e32 v36, v34
	v_mov_b32_e32 v37, v34
	v_mov_b32_e32 v38, v34
	v_mov_b32_e32 v39, v34
	v_mov_b32_e32 v40, v34
	v_mov_b32_e32 v41, v34
	v_mov_b32_e32 v42, v34
	v_mfma_f32_32x32x16_bf16 v[2:17], v[44:47], v[70:73], v[2:17]
	v_mov_b32_e32 v43, v34
	v_mov_b32_e32 v44, v34
	v_mov_b32_e32 v45, v34
	v_mov_b32_e32 v46, v34
	v_mov_b32_e32 v47, v34
	v_mov_b32_e32 v48, v34
	v_mov_b32_e32 v49, v34
	ds_read_b128 v[68:71], v130 offset:16
	ds_read_b128 v[140:143], v133
	s_waitcnt lgkmcnt(2)
	v_mfma_f32_32x32x16_bf16 v[50:65], v[74:77], v[82:85], v[34:49]
	s_waitcnt lgkmcnt(1)
	v_mfma_f32_32x32x16_bf16 v[50:65], v[68:71], v[86:89], v[50:65]
	ds_read_b128 v[68:71], v130 offset:32
	s_waitcnt lgkmcnt(0)
	v_mfma_f32_32x32x16_bf16 v[50:65], v[68:71], v[90:93], v[50:65]
	ds_read_b128 v[68:71], v130 offset:48
	s_waitcnt lgkmcnt(0)
	v_mfma_f32_32x32x16_bf16 v[50:65], v[68:71], v[94:97], v[50:65]
	v_mfma_f32_32x32x16_bf16 v[66:81], v[140:143], v[82:85], v[34:49]
	ds_read_b128 v[140:143], v133 offset:16
	s_nop 9
	v_max_f32_e32 v118, v51, v51
	s_waitcnt lgkmcnt(0)
	v_mfma_f32_32x32x16_bf16 v[66:81], v[140:143], v[86:89], v[66:81]
	ds_read_b128 v[140:143], v133 offset:32
	s_waitcnt lgkmcnt(0)
	v_mfma_f32_32x32x16_bf16 v[66:81], v[140:143], v[90:93], v[66:81]
	ds_read_b128 v[140:143], v133 offset:48
	s_waitcnt lgkmcnt(0)
	v_mfma_f32_32x32x16_bf16 v[66:81], v[140:143], v[94:97], v[66:81]
	s_nop 11
	v_max3_f32 v118, v67, v118, v52
	v_max3_f32 v119, v58, v74, v59
	v_max3_f32 v118, v118, v68, v53
	v_max3_f32 v119, v119, v75, v60
	v_max3_f32 v118, v118, v69, v66
	v_max3_f32 v119, v119, v76, v61
	v_max3_f32 v118, v118, v50, v54
	v_max3_f32 v119, v119, v77, v62
	v_max3_f32 v118, v118, v70, v55
	v_max3_f32 v119, v119, v78, v63
	v_max3_f32 v118, v118, v71, v56
	v_max3_f32 v119, v119, v79, v64
	v_max3_f32 v118, v118, v72, v57
	v_max3_f32 v119, v119, v80, v65
	v_max3_f32 v118, v118, v73, v73
	v_max3_f32 v119, v119, v81, v81
	v_max_f32_e32 v118, v118, v119
	v_mov_b32_e32 v119, v118
	s_nop 1
	v_permlane32_swap_b32_e32 v118, v119
	v_max_f32_e32 v119, v119, v119
	v_max_f32_e32 v118, v118, v118
	v_max_f32_e32 v118, v118, v119
	v_cmp_lt_f32_e32 vcc, s57, v118
	s_cbranch_vccz .LBB0_866
	v_max_f32_e32 v34, v118, v118
	v_max_f32_e32 v36, 0, v34
	v_exp_f32_e64 v38, -v36
	v_add_f32_e32 v123, v123, v36
	v_xor_b32_e32 v34, 0x80000000, v123
	v_pk_add_f32 v[66:67], v[66:67], v[36:37] op_sel_hi:[1,0] neg_lo:[0,1] neg_hi:[0,1]
	v_mul_f32_e32 v139, v139, v38
	v_pk_add_f32 v[50:51], v[50:51], v[36:37] op_sel_hi:[1,0] neg_lo:[0,1] neg_hi:[0,1]
	v_pk_add_f32 v[68:69], v[68:69], v[36:37] op_sel_hi:[1,0] neg_lo:[0,1] neg_hi:[0,1]
	v_pk_add_f32 v[52:53], v[52:53], v[36:37] op_sel_hi:[1,0] neg_lo:[0,1] neg_hi:[0,1]
	v_pk_add_f32 v[70:71], v[70:71], v[36:37] op_sel_hi:[1,0] neg_lo:[0,1] neg_hi:[0,1]
	v_pk_add_f32 v[54:55], v[54:55], v[36:37] op_sel_hi:[1,0] neg_lo:[0,1] neg_hi:[0,1]
	v_pk_add_f32 v[72:73], v[72:73], v[36:37] op_sel_hi:[1,0] neg_lo:[0,1] neg_hi:[0,1]
	v_pk_add_f32 v[56:57], v[56:57], v[36:37] op_sel_hi:[1,0] neg_lo:[0,1] neg_hi:[0,1]
	v_pk_add_f32 v[74:75], v[74:75], v[36:37] op_sel_hi:[1,0] neg_lo:[0,1] neg_hi:[0,1]
	v_pk_add_f32 v[58:59], v[58:59], v[36:37] op_sel_hi:[1,0] neg_lo:[0,1] neg_hi:[0,1]
	v_pk_add_f32 v[76:77], v[76:77], v[36:37] op_sel_hi:[1,0] neg_lo:[0,1] neg_hi:[0,1]
	v_pk_add_f32 v[60:61], v[60:61], v[36:37] op_sel_hi:[1,0] neg_lo:[0,1] neg_hi:[0,1]
	v_pk_add_f32 v[78:79], v[78:79], v[36:37] op_sel_hi:[1,0] neg_lo:[0,1] neg_hi:[0,1]
	v_pk_add_f32 v[62:63], v[62:63], v[36:37] op_sel_hi:[1,0] neg_lo:[0,1] neg_hi:[0,1]
	v_pk_add_f32 v[80:81], v[80:81], v[36:37] op_sel_hi:[1,0] neg_lo:[0,1] neg_hi:[0,1]
	v_pk_add_f32 v[64:65], v[64:65], v[36:37] op_sel_hi:[1,0] neg_lo:[0,1] neg_hi:[0,1]
	v_pk_mul_f32 v[32:33], v[32:33], v[38:39] op_sel_hi:[1,0]
	v_pk_mul_f32 v[30:31], v[30:31], v[38:39] op_sel_hi:[1,0]
	v_pk_mul_f32 v[28:29], v[28:29], v[38:39] op_sel_hi:[1,0]
	v_pk_mul_f32 v[26:27], v[26:27], v[38:39] op_sel_hi:[1,0]
	v_pk_mul_f32 v[24:25], v[24:25], v[38:39] op_sel_hi:[1,0]
	v_pk_mul_f32 v[22:23], v[22:23], v[38:39] op_sel_hi:[1,0]
	v_pk_mul_f32 v[20:21], v[20:21], v[38:39] op_sel_hi:[1,0]
	v_pk_mul_f32 v[18:19], v[18:19], v[38:39] op_sel_hi:[1,0]
	v_pk_mul_f32 v[16:17], v[16:17], v[38:39] op_sel_hi:[1,0]
	v_pk_mul_f32 v[14:15], v[14:15], v[38:39] op_sel_hi:[1,0]
	v_pk_mul_f32 v[12:13], v[12:13], v[38:39] op_sel_hi:[1,0]
	v_pk_mul_f32 v[10:11], v[10:11], v[38:39] op_sel_hi:[1,0]
	v_pk_mul_f32 v[8:9], v[8:9], v[38:39] op_sel_hi:[1,0]
	v_pk_mul_f32 v[6:7], v[6:7], v[38:39] op_sel_hi:[1,0]
	v_pk_mul_f32 v[4:5], v[4:5], v[38:39] op_sel_hi:[1,0]
	v_pk_mul_f32 v[2:3], v[2:3], v[38:39] op_sel_hi:[1,0]
	v_mov_b32_e32 v35, v34
	v_mov_b32_e32 v36, v34
	v_mov_b32_e32 v37, v34
	v_mov_b32_e32 v38, v34
	v_mov_b32_e32 v39, v34
	v_mov_b32_e32 v40, v34
	v_mov_b32_e32 v41, v34
	v_mov_b32_e32 v42, v34
	v_mov_b32_e32 v43, v34
	v_mov_b32_e32 v44, v34
	v_mov_b32_e32 v45, v34
	v_mov_b32_e32 v46, v34
	v_mov_b32_e32 v47, v34
	v_mov_b32_e32 v48, v34
	v_mov_b32_e32 v49, v34
.LBB0_866:
	v_exp_f32_e32 v148, v66
	v_exp_f32_e32 v149, v50
	v_exp_f32_e32 v140, v67
	v_exp_f32_e32 v118, v51
	v_mov_b32_e32 v141, v1
	v_add_f32_e32 v119, v149, v148
	v_exp_f32_e32 v150, v52
	v_pk_add_f32 v[50:51], v[118:119], v[140:141]
	v_exp_f32_e32 v141, v68
	v_pk_add_f32 v[142:143], v[50:51], v[50:51] op_sel_hi:[0,1]
	v_exp_f32_e32 v142, v69
	v_exp_f32_e32 v50, v53
	v_add_f32_e32 v51, v150, v141
	v_exp_f32_e32 v66, v55
	v_exp_f32_e32 v68, v57
	v_pk_add_f32 v[52:53], v[50:51], v[142:143]
	v_exp_f32_e32 v51, v70
	v_pk_add_f32 v[144:145], v[52:53], v[52:53] op_sel_hi:[0,1]
	v_exp_f32_e32 v143, v54
	v_exp_f32_e32 v144, v71
	v_exp_f32_e32 v151, v58
	v_add_u32_e32 v115, 0x1c800, v115
	v_add_f32_e32 v67, v143, v51
	v_pk_add_f32 v[52:53], v[66:67], v[144:145]
	v_exp_f32_e32 v67, v72
	v_pk_add_f32 v[70:71], v[52:53], v[52:53] op_sel_hi:[0,1]
	v_exp_f32_e32 v145, v56
	v_exp_f32_e32 v70, v73
	v_add_f32_e32 v69, v145, v67
	v_pk_add_f32 v[52:53], v[68:69], v[70:71]
	v_exp_f32_e32 v69, v74
	v_pk_add_f32 v[146:147], v[52:53], v[52:53] op_sel_hi:[0,1]
	v_exp_f32_e32 v146, v75
	v_exp_f32_e32 v52, v59
	v_add_f32_e32 v53, v151, v69
	v_pk_add_f32 v[54:55], v[52:53], v[146:147]
	s_nop 0
	v_pk_add_f32 v[74:75], v[54:55], v[54:55] op_sel_hi:[0,1]
	v_exp_f32_e32 v53, v76
	v_exp_f32_e32 v147, v60
	v_exp_f32_e32 v74, v77
	v_exp_f32_e32 v54, v61
	v_add_f32_e32 v55, v147, v53
	v_pk_add_f32 v[56:57], v[54:55], v[74:75]
	s_nop 0
	v_pk_add_f32 v[76:77], v[56:57], v[56:57] op_sel_hi:[0,1]
	v_exp_f32_e32 v55, v78
	v_exp_f32_e32 v75, v62
	v_exp_f32_e32 v76, v79
	v_exp_f32_e32 v56, v63
	v_add_f32_e32 v57, v75, v55
	v_pk_add_f32 v[58:59], v[56:57], v[76:77]
	s_nop 0
	v_pk_add_f32 v[78:79], v[58:59], v[58:59] op_sel_hi:[0,1]
	v_exp_f32_e32 v57, v80
	v_exp_f32_e32 v77, v64
	v_exp_f32_e32 v78, v81
	v_exp_f32_e32 v58, v65
	v_add_f32_e32 v59, v77, v57
	v_pk_add_f32 v[60:61], v[58:59], v[78:79]
	s_nop 0
	v_pk_add_f32 v[60:61], v[60:61], v[60:61] op_sel:[0,1] op_sel_hi:[1,0]
	s_nop 0
	v_mov_b32_e32 v59, v60
	s_nop 1
	v_permlane32_swap_b32_e32 v60, v59
	v_add_f32_e32 v59, v60, v59
	v_cvt_pk_bf16_f32 v60, v148, v140
	v_cvt_pk_bf16_f32 v61, v141, v142
	v_cvt_pk_bf16_f32 v62, v51, v144
	v_cvt_pk_bf16_f32 v63, v67, v70
	ds_read_b64_tr_b16 v[70:71], v115
	ds_read_b64_tr_b16 v[72:73], v115 offset:1152
	s_waitcnt lgkmcnt(0)
	v_mfma_f32_32x32x16_bf16 v[18:33], v[70:73], v[60:63], v[18:33]
	ds_read_b64_tr_b16 v[70:71], v115 offset:64
	ds_read_b64_tr_b16 v[72:73], v115 offset:1216
	v_add_f32_e32 v119, v139, v59
	s_waitcnt lgkmcnt(0)
	v_mfma_f32_32x32x16_bf16 v[2:17], v[70:73], v[60:63], v[2:17]
	v_cvt_pk_bf16_f32 v60, v69, v146
	v_cvt_pk_bf16_f32 v61, v53, v74
	v_cvt_pk_bf16_f32 v62, v55, v76
	v_cvt_pk_bf16_f32 v63, v57, v78
	ds_read_b64_tr_b16 v[70:71], v115 offset:2304
	ds_read_b64_tr_b16 v[72:73], v115 offset:3456
	s_waitcnt lgkmcnt(0)
	v_mfma_f32_32x32x16_bf16 v[18:33], v[70:73], v[60:63], v[18:33]
	ds_read_b64_tr_b16 v[70:71], v115 offset:2368
	ds_read_b64_tr_b16 v[72:73], v115 offset:3520
	s_waitcnt lgkmcnt(0)
	v_mfma_f32_32x32x16_bf16 v[2:17], v[70:73], v[60:63], v[2:17]
	v_cvt_pk_bf16_f32 v60, v149, v118
	v_cvt_pk_bf16_f32 v61, v150, v50
	v_cvt_pk_bf16_f32 v62, v143, v66
	v_cvt_pk_bf16_f32 v63, v145, v68
	ds_read_b64_tr_b16 v[64:65], v115 offset:4608
	ds_read_b64_tr_b16 v[66:67], v115 offset:5760
	s_waitcnt lgkmcnt(0)
	v_mfma_f32_32x32x16_bf16 v[18:33], v[64:67], v[60:63], v[18:33]
	ds_read_b64_tr_b16 v[64:65], v115 offset:4672
	ds_read_b64_tr_b16 v[66:67], v115 offset:5824
	v_cvt_pk_bf16_f32 v50, v151, v52
	v_cvt_pk_bf16_f32 v51, v147, v54
	v_cvt_pk_bf16_f32 v52, v75, v56
	v_cvt_pk_bf16_f32 v53, v77, v58
	ds_read_b64_tr_b16 v[54:55], v115 offset:6912
	ds_read_b64_tr_b16 v[56:57], v115 offset:8064
	s_waitcnt lgkmcnt(2)
	v_mfma_f32_32x32x16_bf16 v[2:17], v[64:67], v[60:63], v[2:17]
	s_waitcnt lgkmcnt(0)
	v_mfma_f32_32x32x16_bf16 v[18:33], v[54:57], v[50:53], v[18:33]
	ds_read_b64_tr_b16 v[54:55], v115 offset:6976
	ds_read_b64_tr_b16 v[56:57], v115 offset:8128
	s_waitcnt vmcnt(3)
	ds_write_b128 v136, v[106:109]
	s_waitcnt vmcnt(2)
	ds_write_b128 v137, v[110:113]
	s_waitcnt lgkmcnt(0)
	s_barrier
	ds_read_b128 v[106:109], v138
	ds_read_b128 v[110:113], v138 offset:16
	ds_read_b128 v[140:143], v138 offset:32
	ds_read_b128 v[136:139], v138 offset:48
	ds_read_b128 v[66:69], v135
	ds_read_b128 v[70:73], v135 offset:16
	ds_read_b128 v[74:77], v135 offset:32
	ds_read_b128 v[78:81], v135 offset:48
	v_mfma_f32_32x32x16_bf16 v[2:17], v[54:57], v[50:53], v[2:17]
	s_waitcnt lgkmcnt(3)
	v_mfma_f32_32x32x16_bf16 v[50:65], v[66:69], v[82:85], v[34:49]
	s_waitcnt lgkmcnt(2)
	v_mfma_f32_32x32x16_bf16 v[50:65], v[70:73], v[86:89], v[50:65]
	s_waitcnt lgkmcnt(1)
	v_mfma_f32_32x32x16_bf16 v[50:65], v[74:77], v[90:93], v[50:65]
	s_waitcnt lgkmcnt(0)
	v_mfma_f32_32x32x16_bf16 v[50:65], v[78:81], v[94:97], v[50:65]
	v_mfma_f32_32x32x16_bf16 v[66:81], v[106:109], v[82:85], v[34:49]
	s_nop 10
	v_max_f32_e32 v106, v51, v51
	v_mfma_f32_32x32x16_bf16 v[66:81], v[110:113], v[86:89], v[66:81]
	v_mfma_f32_32x32x16_bf16 v[66:81], v[140:143], v[90:93], v[66:81]
	v_mfma_f32_32x32x16_bf16 v[66:81], v[136:139], v[94:97], v[66:81]
	s_nop 11
	v_max3_f32 v106, v67, v106, v52
	v_max3_f32 v107, v58, v74, v59
	v_max3_f32 v106, v106, v68, v53
	v_max3_f32 v107, v107, v75, v60
	v_max3_f32 v106, v106, v69, v66
	v_max3_f32 v107, v107, v76, v61
	v_max3_f32 v106, v106, v50, v54
	v_max3_f32 v107, v107, v77, v62
	v_max3_f32 v106, v106, v70, v55
	v_max3_f32 v107, v107, v78, v63
	v_max3_f32 v106, v106, v71, v56
	v_max3_f32 v107, v107, v79, v64
	v_max3_f32 v106, v106, v72, v57
	v_max3_f32 v107, v107, v80, v65
	v_max3_f32 v106, v106, v73, v73
	v_max3_f32 v107, v107, v81, v81
	v_max_f32_e32 v106, v106, v107
	v_mov_b32_e32 v107, v106
	s_nop 1
	v_permlane32_swap_b32_e32 v106, v107
	v_max_f32_e32 v107, v107, v107
	v_max_f32_e32 v106, v106, v106
	v_max_f32_e32 v106, v106, v107
	v_cmp_lt_f32_e32 vcc, s57, v106
	s_cbranch_vccz .LBB0_868
	v_max_f32_e32 v34, v106, v106
	v_max_f32_e32 v36, 0, v34
	v_exp_f32_e64 v38, -v36
	v_add_f32_e32 v123, v123, v36
	v_xor_b32_e32 v34, 0x80000000, v123
	v_pk_add_f32 v[66:67], v[66:67], v[36:37] op_sel_hi:[1,0] neg_lo:[0,1] neg_hi:[0,1]
	v_mul_f32_e32 v119, v119, v38
	v_pk_add_f32 v[50:51], v[50:51], v[36:37] op_sel_hi:[1,0] neg_lo:[0,1] neg_hi:[0,1]
	v_pk_add_f32 v[68:69], v[68:69], v[36:37] op_sel_hi:[1,0] neg_lo:[0,1] neg_hi:[0,1]
	v_pk_add_f32 v[52:53], v[52:53], v[36:37] op_sel_hi:[1,0] neg_lo:[0,1] neg_hi:[0,1]
	v_pk_add_f32 v[70:71], v[70:71], v[36:37] op_sel_hi:[1,0] neg_lo:[0,1] neg_hi:[0,1]
	v_pk_add_f32 v[54:55], v[54:55], v[36:37] op_sel_hi:[1,0] neg_lo:[0,1] neg_hi:[0,1]
	v_pk_add_f32 v[72:73], v[72:73], v[36:37] op_sel_hi:[1,0] neg_lo:[0,1] neg_hi:[0,1]
	v_pk_add_f32 v[56:57], v[56:57], v[36:37] op_sel_hi:[1,0] neg_lo:[0,1] neg_hi:[0,1]
	v_pk_add_f32 v[74:75], v[74:75], v[36:37] op_sel_hi:[1,0] neg_lo:[0,1] neg_hi:[0,1]
	v_pk_add_f32 v[58:59], v[58:59], v[36:37] op_sel_hi:[1,0] neg_lo:[0,1] neg_hi:[0,1]
	v_pk_add_f32 v[76:77], v[76:77], v[36:37] op_sel_hi:[1,0] neg_lo:[0,1] neg_hi:[0,1]
	v_pk_add_f32 v[60:61], v[60:61], v[36:37] op_sel_hi:[1,0] neg_lo:[0,1] neg_hi:[0,1]
	v_pk_add_f32 v[78:79], v[78:79], v[36:37] op_sel_hi:[1,0] neg_lo:[0,1] neg_hi:[0,1]
	v_pk_add_f32 v[62:63], v[62:63], v[36:37] op_sel_hi:[1,0] neg_lo:[0,1] neg_hi:[0,1]
	v_pk_add_f32 v[80:81], v[80:81], v[36:37] op_sel_hi:[1,0] neg_lo:[0,1] neg_hi:[0,1]
	v_pk_add_f32 v[64:65], v[64:65], v[36:37] op_sel_hi:[1,0] neg_lo:[0,1] neg_hi:[0,1]
	v_pk_mul_f32 v[32:33], v[32:33], v[38:39] op_sel_hi:[1,0]
	v_pk_mul_f32 v[30:31], v[30:31], v[38:39] op_sel_hi:[1,0]
	v_pk_mul_f32 v[28:29], v[28:29], v[38:39] op_sel_hi:[1,0]
	v_pk_mul_f32 v[26:27], v[26:27], v[38:39] op_sel_hi:[1,0]
	v_pk_mul_f32 v[24:25], v[24:25], v[38:39] op_sel_hi:[1,0]
	v_pk_mul_f32 v[22:23], v[22:23], v[38:39] op_sel_hi:[1,0]
	v_pk_mul_f32 v[20:21], v[20:21], v[38:39] op_sel_hi:[1,0]
	v_pk_mul_f32 v[18:19], v[18:19], v[38:39] op_sel_hi:[1,0]
	v_pk_mul_f32 v[16:17], v[16:17], v[38:39] op_sel_hi:[1,0]
	v_pk_mul_f32 v[14:15], v[14:15], v[38:39] op_sel_hi:[1,0]
	v_pk_mul_f32 v[12:13], v[12:13], v[38:39] op_sel_hi:[1,0]
	v_pk_mul_f32 v[10:11], v[10:11], v[38:39] op_sel_hi:[1,0]
	v_pk_mul_f32 v[8:9], v[8:9], v[38:39] op_sel_hi:[1,0]
	v_pk_mul_f32 v[6:7], v[6:7], v[38:39] op_sel_hi:[1,0]
	v_pk_mul_f32 v[4:5], v[4:5], v[38:39] op_sel_hi:[1,0]
	v_pk_mul_f32 v[2:3], v[2:3], v[38:39] op_sel_hi:[1,0]
	v_mov_b32_e32 v35, v34
	v_mov_b32_e32 v36, v34
	v_mov_b32_e32 v37, v34
	v_mov_b32_e32 v38, v34
	v_mov_b32_e32 v39, v34
	v_mov_b32_e32 v40, v34
	v_mov_b32_e32 v41, v34
	v_mov_b32_e32 v42, v34
	v_mov_b32_e32 v43, v34
	v_mov_b32_e32 v44, v34
	v_mov_b32_e32 v45, v34
	v_mov_b32_e32 v46, v34
	v_mov_b32_e32 v47, v34
	v_mov_b32_e32 v48, v34
	v_mov_b32_e32 v49, v34
.LBB0_868:
	v_exp_f32_e32 v118, v66
	v_exp_f32_e32 v135, v50
	v_exp_f32_e32 v108, v67
	v_exp_f32_e32 v106, v51
	v_mov_b32_e32 v109, v1
	v_add_f32_e32 v107, v135, v118
	v_exp_f32_e32 v138, v52
	v_pk_add_f32 v[50:51], v[106:107], v[108:109]
	v_exp_f32_e32 v109, v68
	v_pk_add_f32 v[110:111], v[50:51], v[50:51] op_sel_hi:[0,1]
	v_exp_f32_e32 v110, v69
	v_exp_f32_e32 v50, v53
	v_add_f32_e32 v51, v138, v109
	v_exp_f32_e32 v66, v55
	v_exp_f32_e32 v68, v57
	v_pk_add_f32 v[52:53], v[50:51], v[110:111]
	v_exp_f32_e32 v51, v70
	v_pk_add_f32 v[112:113], v[52:53], v[52:53] op_sel_hi:[0,1]
	v_exp_f32_e32 v111, v54
	v_exp_f32_e32 v112, v71
	v_exp_f32_e32 v139, v58
	v_add_f32_e32 v67, v111, v51
	v_pk_add_f32 v[52:53], v[66:67], v[112:113]
	v_exp_f32_e32 v67, v72
	v_pk_add_f32 v[70:71], v[52:53], v[52:53] op_sel_hi:[0,1]
	v_exp_f32_e32 v113, v56
	v_exp_f32_e32 v70, v73
	v_add_f32_e32 v69, v113, v67
	v_pk_add_f32 v[52:53], v[68:69], v[70:71]
	v_exp_f32_e32 v69, v74
	v_pk_add_f32 v[136:137], v[52:53], v[52:53] op_sel_hi:[0,1]
	v_exp_f32_e32 v136, v75
	v_exp_f32_e32 v52, v59
	v_add_f32_e32 v53, v139, v69
	v_pk_add_f32 v[54:55], v[52:53], v[136:137]
	s_nop 0
	v_pk_add_f32 v[74:75], v[54:55], v[54:55] op_sel_hi:[0,1]
	v_exp_f32_e32 v53, v76
	v_exp_f32_e32 v137, v60
	v_exp_f32_e32 v74, v77
	v_exp_f32_e32 v54, v61
	v_add_f32_e32 v55, v137, v53
	v_pk_add_f32 v[56:57], v[54:55], v[74:75]
	s_nop 0
	v_pk_add_f32 v[76:77], v[56:57], v[56:57] op_sel_hi:[0,1]
	v_exp_f32_e32 v55, v78
	v_exp_f32_e32 v75, v62
	v_exp_f32_e32 v76, v79
	v_exp_f32_e32 v56, v63
	v_add_f32_e32 v57, v75, v55
	v_pk_add_f32 v[58:59], v[56:57], v[76:77]
	s_nop 0
	v_pk_add_f32 v[78:79], v[58:59], v[58:59] op_sel_hi:[0,1]
	v_exp_f32_e32 v57, v80
	v_exp_f32_e32 v77, v64
	v_exp_f32_e32 v78, v81
	v_exp_f32_e32 v58, v65
	v_add_f32_e32 v59, v77, v57
	v_pk_add_f32 v[60:61], v[58:59], v[78:79]
	s_nop 0
	v_pk_add_f32 v[60:61], v[60:61], v[60:61] op_sel:[0,1] op_sel_hi:[1,0]
	s_nop 0
	v_mov_b32_e32 v59, v60
	s_nop 1
	v_permlane32_swap_b32_e32 v60, v59
	v_add_f32_e32 v59, v60, v59
	v_cvt_pk_bf16_f32 v60, v118, v108
	v_cvt_pk_bf16_f32 v61, v109, v110
	v_cvt_pk_bf16_f32 v62, v51, v112
	v_cvt_pk_bf16_f32 v63, v67, v70
	ds_read_b64_tr_b16 v[70:71], v129
	ds_read_b64_tr_b16 v[72:73], v129 offset:1152
	s_waitcnt lgkmcnt(0)
	v_mfma_f32_32x32x16_bf16 v[18:33], v[70:73], v[60:63], v[18:33]
	ds_read_b64_tr_b16 v[70:71], v129 offset:64
	ds_read_b64_tr_b16 v[72:73], v129 offset:1216
	v_add_f32_e32 v107, v119, v59
	s_waitcnt lgkmcnt(0)
	v_mfma_f32_32x32x16_bf16 v[2:17], v[70:73], v[60:63], v[2:17]
	v_cvt_pk_bf16_f32 v60, v69, v136
	v_cvt_pk_bf16_f32 v61, v53, v74
	v_cvt_pk_bf16_f32 v62, v55, v76
	v_cvt_pk_bf16_f32 v63, v57, v78
	ds_read_b64_tr_b16 v[70:71], v129 offset:2304
	ds_read_b64_tr_b16 v[72:73], v129 offset:3456
	s_waitcnt lgkmcnt(0)
	v_mfma_f32_32x32x16_bf16 v[18:33], v[70:73], v[60:63], v[18:33]
	ds_read_b64_tr_b16 v[70:71], v129 offset:2368
	ds_read_b64_tr_b16 v[72:73], v129 offset:3520
	s_waitcnt lgkmcnt(0)
	v_mfma_f32_32x32x16_bf16 v[2:17], v[70:73], v[60:63], v[2:17]
	v_cvt_pk_bf16_f32 v60, v135, v106
	v_cvt_pk_bf16_f32 v61, v138, v50
	v_cvt_pk_bf16_f32 v62, v111, v66
	v_cvt_pk_bf16_f32 v63, v113, v68
	ds_read_b64_tr_b16 v[64:65], v129 offset:4608
	ds_read_b64_tr_b16 v[66:67], v129 offset:5760
	s_waitcnt lgkmcnt(0)
	v_mfma_f32_32x32x16_bf16 v[18:33], v[64:67], v[60:63], v[18:33]
	ds_read_b64_tr_b16 v[64:65], v129 offset:4672
	ds_read_b64_tr_b16 v[66:67], v129 offset:5824
	v_cvt_pk_bf16_f32 v50, v139, v52
	v_cvt_pk_bf16_f32 v51, v137, v54
	v_cvt_pk_bf16_f32 v52, v75, v56
	v_cvt_pk_bf16_f32 v53, v77, v58
	ds_read_b64_tr_b16 v[54:55], v129 offset:6912
	ds_read_b64_tr_b16 v[56:57], v129 offset:8064
	s_waitcnt lgkmcnt(2)
	v_mfma_f32_32x32x16_bf16 v[2:17], v[64:67], v[60:63], v[2:17]
	s_waitcnt lgkmcnt(0)
	v_mfma_f32_32x32x16_bf16 v[18:33], v[54:57], v[50:53], v[18:33]
	ds_read_b64_tr_b16 v[54:55], v129 offset:6976
	ds_read_b64_tr_b16 v[56:57], v129 offset:8128
	s_waitcnt vmcnt(1)
	ds_write_b128 v131, v[98:101]
	s_waitcnt vmcnt(0)
	ds_write_b128 v132, v[102:105]
	s_waitcnt lgkmcnt(0)
	s_barrier
	ds_read_b128 v[66:69], v133
	ds_read_b128 v[70:73], v133 offset:16
	ds_read_b128 v[74:77], v133 offset:32
	ds_read_b128 v[78:81], v133 offset:48
	ds_read_b128 v[98:101], v130
	ds_read_b128 v[102:105], v130 offset:16
	ds_read_b128 v[108:111], v130 offset:32
	ds_read_b128 v[130:133], v130 offset:48
	v_mfma_f32_32x32x16_bf16 v[2:17], v[54:57], v[50:53], v[2:17]
	s_waitcnt lgkmcnt(3)
	v_mfma_f32_32x32x16_bf16 v[50:65], v[98:101], v[82:85], v[34:49]
	v_mfma_f32_32x32x16_bf16 v[34:49], v[66:69], v[82:85], v[34:49]
	s_waitcnt lgkmcnt(2)
	v_mfma_f32_32x32x16_bf16 v[50:65], v[102:105], v[86:89], v[50:65]
	v_mfma_f32_32x32x16_bf16 v[34:49], v[70:73], v[86:89], v[34:49]
	s_waitcnt lgkmcnt(1)
	v_mfma_f32_32x32x16_bf16 v[50:65], v[108:111], v[90:93], v[50:65]
	v_mfma_f32_32x32x16_bf16 v[34:49], v[74:77], v[90:93], v[34:49]
	s_waitcnt lgkmcnt(0)
	v_mfma_f32_32x32x16_bf16 v[50:65], v[130:133], v[94:97], v[50:65]
	v_mfma_f32_32x32x16_bf16 v[34:49], v[78:81], v[94:97], v[34:49]
	s_nop 10
	v_max3_f32 v66, v51, v35, v52
	v_max3_f32 v67, v58, v42, v59
	v_max3_f32 v66, v66, v36, v53
	v_max3_f32 v67, v67, v43, v60
	v_max3_f32 v66, v66, v37, v34
	v_max3_f32 v67, v67, v44, v61
	v_max3_f32 v66, v66, v50, v54
	v_max3_f32 v67, v67, v45, v62
	v_max3_f32 v66, v66, v38, v55
	v_max3_f32 v67, v67, v46, v63
	v_max3_f32 v66, v66, v39, v56
	v_max3_f32 v67, v67, v47, v64
	v_max3_f32 v66, v66, v40, v57
	v_max3_f32 v67, v67, v48, v65
	v_max3_f32 v66, v66, v41, v41
	v_max3_f32 v67, v67, v49, v49
	v_max_f32_e32 v66, v66, v67
	v_mov_b32_e32 v67, v66
	s_nop 1
	v_permlane32_swap_b32_e32 v66, v67
	v_max_f32_e32 v67, v67, v67
	v_max_f32_e32 v66, v66, v66
	v_max_f32_e32 v66, v66, v67
	v_cmp_lt_f32_e32 vcc, s57, v66
	s_cbranch_vccz .LBB0_870
	v_max_f32_e32 v66, v66, v66
	v_max_f32_e32 v66, 0, v66
	v_exp_f32_e64 v68, -v66
	v_add_f32_e32 v123, v123, v66
	v_pk_add_f32 v[34:35], v[34:35], v[66:67] op_sel_hi:[1,0] neg_lo:[0,1] neg_hi:[0,1]
	v_pk_add_f32 v[50:51], v[50:51], v[66:67] op_sel_hi:[1,0] neg_lo:[0,1] neg_hi:[0,1]
	v_mul_f32_e32 v107, v107, v68
	v_pk_add_f32 v[36:37], v[36:37], v[66:67] op_sel_hi:[1,0] neg_lo:[0,1] neg_hi:[0,1]
	v_pk_add_f32 v[52:53], v[52:53], v[66:67] op_sel_hi:[1,0] neg_lo:[0,1] neg_hi:[0,1]
	v_pk_add_f32 v[38:39], v[38:39], v[66:67] op_sel_hi:[1,0] neg_lo:[0,1] neg_hi:[0,1]
	v_pk_add_f32 v[54:55], v[54:55], v[66:67] op_sel_hi:[1,0] neg_lo:[0,1] neg_hi:[0,1]
	v_pk_add_f32 v[40:41], v[40:41], v[66:67] op_sel_hi:[1,0] neg_lo:[0,1] neg_hi:[0,1]
	v_pk_add_f32 v[56:57], v[56:57], v[66:67] op_sel_hi:[1,0] neg_lo:[0,1] neg_hi:[0,1]
	v_pk_add_f32 v[42:43], v[42:43], v[66:67] op_sel_hi:[1,0] neg_lo:[0,1] neg_hi:[0,1]
	v_pk_add_f32 v[58:59], v[58:59], v[66:67] op_sel_hi:[1,0] neg_lo:[0,1] neg_hi:[0,1]
	v_pk_add_f32 v[44:45], v[44:45], v[66:67] op_sel_hi:[1,0] neg_lo:[0,1] neg_hi:[0,1]
	v_pk_add_f32 v[60:61], v[60:61], v[66:67] op_sel_hi:[1,0] neg_lo:[0,1] neg_hi:[0,1]
	v_pk_add_f32 v[46:47], v[46:47], v[66:67] op_sel_hi:[1,0] neg_lo:[0,1] neg_hi:[0,1]
	v_pk_add_f32 v[62:63], v[62:63], v[66:67] op_sel_hi:[1,0] neg_lo:[0,1] neg_hi:[0,1]
	v_pk_add_f32 v[48:49], v[48:49], v[66:67] op_sel_hi:[1,0] neg_lo:[0,1] neg_hi:[0,1]
	v_pk_add_f32 v[64:65], v[64:65], v[66:67] op_sel_hi:[1,0] neg_lo:[0,1] neg_hi:[0,1]
	v_pk_mul_f32 v[32:33], v[32:33], v[68:69] op_sel_hi:[1,0]
	v_pk_mul_f32 v[30:31], v[30:31], v[68:69] op_sel_hi:[1,0]
	v_pk_mul_f32 v[28:29], v[28:29], v[68:69] op_sel_hi:[1,0]
	v_pk_mul_f32 v[26:27], v[26:27], v[68:69] op_sel_hi:[1,0]
	v_pk_mul_f32 v[24:25], v[24:25], v[68:69] op_sel_hi:[1,0]
	v_pk_mul_f32 v[22:23], v[22:23], v[68:69] op_sel_hi:[1,0]
	v_pk_mul_f32 v[20:21], v[20:21], v[68:69] op_sel_hi:[1,0]
	v_pk_mul_f32 v[18:19], v[18:19], v[68:69] op_sel_hi:[1,0]
	v_pk_mul_f32 v[16:17], v[16:17], v[68:69] op_sel_hi:[1,0]
	v_pk_mul_f32 v[14:15], v[14:15], v[68:69] op_sel_hi:[1,0]
	v_pk_mul_f32 v[12:13], v[12:13], v[68:69] op_sel_hi:[1,0]
	v_pk_mul_f32 v[10:11], v[10:11], v[68:69] op_sel_hi:[1,0]
	v_pk_mul_f32 v[8:9], v[8:9], v[68:69] op_sel_hi:[1,0]
	v_pk_mul_f32 v[6:7], v[6:7], v[68:69] op_sel_hi:[1,0]
	v_pk_mul_f32 v[4:5], v[4:5], v[68:69] op_sel_hi:[1,0]
	v_pk_mul_f32 v[2:3], v[2:3], v[68:69] op_sel_hi:[1,0]
